# stagger strategy: waves 4-7 enter the SSM pass-2 scan loop half a step (s_sleep 24) after their SIMD partners; on top of v155
# baseline (speedup 1.0000x reference)
; #define GAS __attribute__((address_space(1)))
; #define LAS __attribute__((address_space(3)))
; __device__ __forceinline__ unsigned cvt2(float lo, float hi) { const f2_t v = {lo, hi}; return __builtin_bit_cast(unsigned, __builtin_convertvector(v, bf2_t)); }
; __device__ __forceinline__ f2v fma2(f2v a, f2v b, f2v c) { return __builtin_elementwise_fma(a, b, c); }
; __device__ __forceinline__ void ssm_phase(Frame& F) {
;     ...
; #pragma unroll 1
;         for (int it = 0; it < 2; ++it) {
;             const int cA = F.wave + 8 * aq + 32 * it;
;             const bf16* arow = ubase + (size_t)(cA * 64 + atk) * SG + 8 * h;
;             bf16x8 afr[8];
; #pragma unroll
;             for (int s = 0; s < 8; ++s) afr[s] = __builtin_nontemporal_load((const GAS bf16x8*)(arow + (size_t)(8 * s) * SG));
;             f2v Sre0, Sim0, Sre1, Sim1;
; #pragma unroll
;             for (int e = 0; e < 2; ++e) { const LAS float* fi_ = FS + (F.wave + 8 * (2 * h + e) + 32 * it) * 128 + l31; Sre0[e] = fi_[0]; Sre1[e] = fi_[32]; Sim0[e] = fi_[64]; Sim1[e] = fi_[96]; }
; #pragma unroll
;             for (int s = 0; s < 8; ++s) {
;                 *(LAS bf16x8*)(ut + l31 * 32 + 16 * h) = afr[s];
;                 const f32x16 D0 = __builtin_amdgcn_mfma_f32_32x32x16_bf16(afr[s], bfrag[0], z, 0, 0, 0), D1 = __builtin_amdgcn_mfma_f32_32x32x16_bf16(afr[s], bfrag[1], z, 0, 0, 0),
;                              D2 = __builtin_amdgcn_mfma_f32_32x32x16_bf16(afr[s], bfrag[2], z, 0, 0, 0), D3 = __builtin_amdgcn_mfma_f32_32x32x16_bf16(afr[s], bfrag[3], z, 0, 0, 0);
; #pragma unroll
;                 for (int t = 0; t < 8; ++t) {
;                     const f2v d0 = {D0[2 * t], D0[2 * t + 1]}, d1 = {D1[2 * t], D1[2 * t + 1]}, d2 = {D2[2 * t], D2[2 * t + 1]}, d3 = {D3[2 * t], D3[2 * t + 1]};
;                     const f2v nr0 = fma2(AR0, Sre0, fma2(NAI0, Sim0, d0)), ni0 = fma2(AR0, Sim0, fma2(AI0, Sre0, d2));
;                     const f2v nr1 = fma2(AR1, Sre1, fma2(NAI1, Sim1, d1)), ni1 = fma2(AR1, Sim1, fma2(AI1, Sre1, d3));
;                     Sre0 = nr0; Sim0 = ni0; Sre1 = nr1; Sim1 = ni1;
; #pragma unroll
;                     for (int e = 0; e < 2; ++e) { v2u w; w.x = cvt2(nr0[e], nr1[e]); w.y = cvt2(ni0[e], ni1[e]); *(LAS v2u*)(st + (16 * h + 2 * t + e) * 272 + 8 * l31) = w; }
;                 }
.LBB0_328:
	s_lshl_b32 s0, s6, 12
	s_lshl_b32 s6, s23, 1
	v_lshl_add_u64 v[124:125], v[156:157], 1, s[2:3]
	v_lshl_add_u64 v[126:127], v[164:165], 0, s[6:7]
	v_or_b32_e32 v138, s0, v199
	v_or_b32_e32 v139, s0, v202
	v_or_b32_e32 v140, s0, v203
	v_or_b32_e32 v141, s0, v204
	v_or_b32_e32 v142, s0, v205
	v_or_b32_e32 v143, s0, v206
	v_or_b32_e32 v144, s0, v207
	v_or_b32_e32 v145, s0, v208
	v_mov_b32_e32 v177, v176
	s_mov_b32 s0, 0
	s_mov_b64 s[2:3], -1
	s_waitcnt lgkmcnt(0)
	s_barrier
	v_readlane_b32 s99, v254, 4
	s_cmp_lt_u32 s99, 0x100
	s_cbranch_scc1 .Lstg2
	s_sleep 24
.Lstg2:
.LBB0_329:
	s_nop 0
	v_cndmask_b32_e64 v0, 0, 1, s[2:3]
	s_add_i32 s0, s0, s33
	v_cmp_ne_u32_e32 vcc, 1, v0
	v_add_u32_e32 v0, s0, v194
	v_lshl_or_b32 v162, v0, 6, v192
	v_lshlrev_b64 v[0:1], 5, v[162:163]
	v_lshl_add_u64 v[0:1], v[124:125], 0, v[0:1]
	global_load_dwordx4 v[16:19], v[0:1], off nt
	global_load_dwordx4 v[120:123], v[0:1], off offset:256 nt
	global_load_dwordx4 v[116:119], v[0:1], off offset:512 nt
	global_load_dwordx4 v[112:115], v[0:1], off offset:768 nt
	global_load_dwordx4 v[108:111], v[0:1], off offset:1024 nt
	global_load_dwordx4 v[104:107], v[0:1], off offset:1280 nt
	global_load_dwordx4 v[100:103], v[0:1], off offset:1536 nt
	global_load_dwordx4 v[96:99], v[0:1], off offset:1792 nt
	v_lshl_add_u32 v4, s0, 9, v209
	ds_read2_b32 v[0:1], v4 offset1:32
	ds_read2_b32 v[2:3], v4 offset0:64 offset1:96
	v_add_u32_e32 v4, 0x1000, v4
	ds_read2_b32 v[128:129], v4 offset1:32
	ds_read2_b32 v[132:133], v4 offset0:64 offset1:96
	s_waitcnt lgkmcnt(3)
	v_mov_b32_e32 v130, v0
	s_waitcnt lgkmcnt(2)
	v_mov_b32_e32 v134, v2
	v_add_u32_e32 v149, 0x8000, v201
	s_waitcnt lgkmcnt(1)
	v_mov_b32_e32 v131, v128
	v_mov_b32_e32 v128, v1
	s_waitcnt lgkmcnt(0)
	v_mov_b32_e32 v135, v132
	v_mov_b32_e32 v132, v3
	v_add_u32_e32 v146, 0x8800, v201
	v_add_u32_e32 v147, s5, v197
	v_add_lshl_u32 v148, s0, v198, 6
	s_mov_b32 s0, 32
	s_mov_b64 s[2:3], 0
	s_and_b64 vcc, exec, vcc
	s_waitcnt vmcnt(7)
	v_mfma_f32_32x32x16_bf16 v[32:47], v[16:19], v[64:67], 0
	ds_write_b128 v212, v[16:19]
	s_nop 10
	v_pk_fma_f32 v[32:33], v[178:179], v[134:135], v[32:33]
	v_mfma_f32_32x32x16_bf16 v[0:15], v[16:19], v[68:71], 0
	v_fma_f32 v32, v168, v130, v32
	v_fma_f32 v33, v169, v131, v33
	v_mfma_f32_32x32x16_bf16 v[48:63], v[16:19], v[72:75], 0
	s_nop 8
	v_fma_f32 v0, v180, v132, v0
	v_fma_f32 v1, v181, v133, v1
	v_fma_f32 v0, v170, v128, v0
	v_fma_f32 v1, v171, v129, v1
	v_mfma_f32_32x32x16_bf16 v[16:31], v[16:19], v[76:79], 0
	v_fma_f32 v48, v172, v130, v48
	v_fma_f32 v49, v173, v131, v49
	v_cvt_pk_bf16_f32 v130, v33, v1
	v_fma_f32 v48, v168, v134, v48
	v_fma_f32 v49, v169, v135, v49
	v_pk_fma_f32 v[34:35], v[178:179], v[48:49], v[34:35]
	s_nop 5
	v_pk_fma_f32 v[16:17], v[174:175], v[128:129], v[16:17]
	s_nop 0
	v_pk_fma_f32 v[16:17], v[170:171], v[132:133], v[16:17]
	v_cvt_pk_bf16_f32 v128, v32, v0
	v_pk_fma_f32 v[2:3], v[180:181], v[16:17], v[2:3]
	v_pk_fma_f32 v[34:35], v[168:169], v[32:33], v[34:35]
	v_pk_fma_f32 v[32:33], v[172:173], v[32:33], v[50:51]
	v_pk_fma_f32 v[2:3], v[170:171], v[0:1], v[2:3]
	v_pk_fma_f32 v[0:1], v[174:175], v[0:1], v[18:19]
	v_pk_fma_f32 v[32:33], v[168:169], v[48:49], v[32:33]
	v_pk_fma_f32 v[0:1], v[170:171], v[16:17], v[0:1]
	v_cvt_pk_bf16_f32 v129, v48, v16
	v_cvt_pk_bf16_f32 v131, v49, v17
	v_cvt_pk_bf16_f32 v16, v34, v2
	v_cvt_pk_bf16_f32 v17, v32, v0
	v_cvt_pk_bf16_f32 v18, v35, v3
	v_cvt_pk_bf16_f32 v19, v33, v1
	v_pk_fma_f32 v[4:5], v[180:181], v[0:1], v[4:5]
	ds_write2_b64 v149, v[16:17], v[18:19] offset0:68 offset1:102
	v_pk_fma_f32 v[16:17], v[178:179], v[32:33], v[36:37]
	v_pk_fma_f32 v[18:19], v[172:173], v[34:35], v[52:53]
	v_pk_fma_f32 v[4:5], v[170:171], v[2:3], v[4:5]
	v_pk_fma_f32 v[2:3], v[174:175], v[2:3], v[20:21]
	v_pk_fma_f32 v[16:17], v[168:169], v[34:35], v[16:17]
	v_pk_fma_f32 v[18:19], v[168:169], v[32:33], v[18:19]
	v_pk_fma_f32 v[0:1], v[170:171], v[0:1], v[2:3]
	v_cvt_pk_bf16_f32 v2, v16, v4
	v_cvt_pk_bf16_f32 v3, v18, v0
	v_cvt_pk_bf16_f32 v20, v17, v5
	v_cvt_pk_bf16_f32 v21, v19, v1
	ds_write2_b64 v149, v[2:3], v[20:21] offset0:136 offset1:170
	v_pk_fma_f32 v[2:3], v[178:179], v[18:19], v[38:39]
	v_pk_fma_f32 v[6:7], v[180:181], v[0:1], v[6:7]
	v_pk_fma_f32 v[2:3], v[168:169], v[16:17], v[2:3]
	v_pk_fma_f32 v[16:17], v[172:173], v[16:17], v[54:55]
	v_pk_fma_f32 v[6:7], v[170:171], v[4:5], v[6:7]
	v_pk_fma_f32 v[4:5], v[174:175], v[4:5], v[22:23]
	v_pk_fma_f32 v[16:17], v[168:169], v[18:19], v[16:17]
	v_pk_fma_f32 v[0:1], v[170:171], v[0:1], v[4:5]
	v_cvt_pk_bf16_f32 v4, v2, v6
	v_cvt_pk_bf16_f32 v5, v16, v0
	v_cvt_pk_bf16_f32 v18, v3, v7
	v_cvt_pk_bf16_f32 v19, v17, v1
	ds_write2_b64 v149, v[4:5], v[18:19] offset0:204 offset1:238
	v_pk_fma_f32 v[4:5], v[178:179], v[16:17], v[40:41]
	v_pk_fma_f32 v[8:9], v[180:181], v[0:1], v[8:9]
	v_pk_fma_f32 v[4:5], v[168:169], v[2:3], v[4:5]
	v_pk_fma_f32 v[2:3], v[172:173], v[2:3], v[56:57]
	v_pk_fma_f32 v[8:9], v[170:171], v[6:7], v[8:9]
	v_pk_fma_f32 v[6:7], v[174:175], v[6:7], v[24:25]
	v_pk_fma_f32 v[2:3], v[168:169], v[16:17], v[2:3]
	v_pk_fma_f32 v[0:1], v[170:171], v[0:1], v[6:7]
	v_cvt_pk_bf16_f32 v6, v4, v8
	v_cvt_pk_bf16_f32 v7, v2, v0
	v_cvt_pk_bf16_f32 v16, v5, v9
	v_cvt_pk_bf16_f32 v17, v3, v1
	ds_write2_b64 v146, v[6:7], v[16:17] offset0:16 offset1:50
	v_pk_fma_f32 v[6:7], v[178:179], v[2:3], v[42:43]
	ds_write2_b64 v149, v[128:129], v[130:131] offset1:34
	v_pk_fma_f32 v[6:7], v[168:169], v[4:5], v[6:7]
	v_pk_fma_f32 v[4:5], v[172:173], v[4:5], v[58:59]
	v_mov_b64_e32 v[128:129], s[22:23]
	v_pk_fma_f32 v[2:3], v[168:169], v[2:3], v[4:5]
	v_pk_fma_f32 v[4:5], v[180:181], v[0:1], v[10:11]
	s_nop 0
	v_pk_fma_f32 v[4:5], v[170:171], v[8:9], v[4:5]
	v_pk_fma_f32 v[8:9], v[174:175], v[8:9], v[26:27]
	v_cvt_pk_bf16_f32 v10, v7, v5
	v_pk_fma_f32 v[0:1], v[170:171], v[0:1], v[8:9]
	v_cvt_pk_bf16_f32 v8, v6, v4
	v_cvt_pk_bf16_f32 v9, v2, v0
	v_cvt_pk_bf16_f32 v11, v3, v1
	ds_write2_b64 v146, v[8:9], v[10:11] offset0:84 offset1:118
	v_pk_fma_f32 v[8:9], v[178:179], v[2:3], v[44:45]
	s_nop 0
	v_pk_fma_f32 v[8:9], v[168:169], v[6:7], v[8:9]
	v_pk_fma_f32 v[6:7], v[172:173], v[6:7], v[60:61]
	s_nop 0
	v_pk_fma_f32 v[2:3], v[168:169], v[2:3], v[6:7]
	v_pk_fma_f32 v[6:7], v[180:181], v[0:1], v[12:13]
	s_nop 0
	v_pk_fma_f32 v[6:7], v[170:171], v[4:5], v[6:7]
	v_pk_fma_f32 v[4:5], v[174:175], v[4:5], v[28:29]
	v_cvt_pk_bf16_f32 v10, v9, v7
	v_pk_fma_f32 v[0:1], v[170:171], v[0:1], v[4:5]
	v_cvt_pk_bf16_f32 v4, v8, v6
	v_cvt_pk_bf16_f32 v5, v2, v0
	v_cvt_pk_bf16_f32 v11, v3, v1
	ds_write2_b64 v146, v[4:5], v[10:11] offset0:152 offset1:186
	v_pk_fma_f32 v[4:5], v[178:179], v[2:3], v[46:47]
	s_waitcnt vmcnt(6)
; #define GAS __attribute__((address_space(1)))
; #define LAS __attribute__((address_space(3)))
; #define LDS_WAIT() asm volatile("s_waitcnt lgkmcnt(0)" ::: "memory")
; __device__ __forceinline__ float bf1(bf16 v) { return __uint_as_float((unsigned)v << 16); }
; __device__ __forceinline__ void ssm_phase(Frame& F) {
;     ...
;                     for (int e = 0; e < 2; ++e) { v2u w; w.x = cvt2(nr0[e], nr1[e]); w.y = cvt2(ni0[e], ni1[e]); *(LAS v2u*)(st + (16 * h + 2 * t + e) * 272 + 8 * l31) = w; }
;                 }
;                 LDS_WAIT(); asm volatile("" ::: "memory");
;                 f32x4 acc0 = (f32x4){0.f, 0.f, 0.f, 0.f}, acc1 = (f32x4){0.f, 0.f, 0.f, 0.f};
; #pragma unroll
;                 for (int ks = 0; ks < 4; ++ks) {
;                     const bf16x8 s0 = *(const LAS bf16x8*)(st + l15 * 272 + 64 * ks + 16 * qq), s1 = *(const LAS bf16x8*)(st + (16 + l15) * 272 + 64 * ks + 16 * qq);
;                     acc0 = __builtin_amdgcn_mfma_f32_16x16x32_bf16(s0, cfrag[ks], acc0, 0, 0, 0); acc1 = __builtin_amdgcn_mfma_f32_16x16x32_bf16(s1, cfrag[ks], acc1, 0, 0, 0); }
;                 float uu[2][4];
; #pragma unroll
;                 for (int rb = 0; rb < 2; ++rb)
; #pragma unroll
;                     for (int i2 = 0; i2 < 4; ++i2) uu[rb][i2] = bf1(*(const LAS bf16*)(ut + (i2 + 4 * rb + 8 * qq) * 32 + 2 * l15));
; #pragma unroll
;                 for (int rb = 0; rb < 2; ++rb)
; #pragma unroll
;                     for (int i2 = 0; i2 < 4; i2 += 2) {
;                         f2v y; y.x = (rb == 0 ? acc0[i2] : acc1[i2]) + dsk * uu[rb][i2]; y.y = (rb == 0 ? acc0[i2 + 1] : acc1[i2 + 1]) + dsk * uu[rb][i2 + 1];
;                         const f2v gq = gelu_tanh2(y); const unsigned w = cvt2(gq.x, gq.y);
;                         *(LAS bf16*)(yt + (16 * rb + 4 * qq + i2) * 32 + 2 * l15) = (bf16)(w & 0xffffu); *(LAS bf16*)(yt + (16 * rb + 4 * qq + i2 + 1) * 32 + 2 * l15) = (bf16)(w >> 16); }
;                 LDS_WAIT(); asm volatile("" ::: "memory");
;                 { const int R = lane >> 1, hf = lane & 1; const v4u yv = *(const LAS v4u*)(yt + lane * 16);
;                   const int chunk = F.wave + 8 * (2 * (R >> 4) + (R & 1)) + 32 * it, tok = 8 * s + ((R & 15) >> 1);
;                   *(GAS v4u*)(gb + ((size_t)(b * SEQ + chunk * 64 + tok)) * SW + g * SG + 8 * hf) = yv; }
;                 LDS_WAIT(); asm volatile("" ::: "memory");
;             }
	v_mfma_f32_32x32x16_bf16 v[32:47], v[120:123], v[76:79], 0
	v_fma_f32 v134, v168, v8, v4
	v_fma_f32 v135, v169, v9, v5
	v_fma_f32 v4, v172, v8, v62
	v_fma_f32 v5, v173, v9, v63
	v_fma_f32 v136, v168, v2, v4
	v_fma_f32 v137, v169, v3, v5
	v_pk_fma_f32 v[2:3], v[180:181], v[0:1], v[14:15]
	s_nop 0
	v_pk_fma_f32 v[132:133], v[170:171], v[6:7], v[2:3]
	v_pk_fma_f32 v[2:3], v[174:175], v[6:7], v[30:31]
	v_mfma_f32_32x32x16_bf16 v[48:63], v[120:123], v[64:67], 0
	v_fma_f32 v130, v170, v0, v2
	v_fma_f32 v131, v171, v1, v3
	v_cvt_pk_bf16_f32 v0, v134, v132
	v_cvt_pk_bf16_f32 v1, v136, v130
	v_cvt_pk_bf16_f32 v2, v135, v133
	v_cvt_pk_bf16_f32 v3, v137, v131
	ds_write2_b64 v146, v[0:1], v[2:3] offset0:220 offset1:254
	s_waitcnt lgkmcnt(0)
	ds_read_b128 v[0:3], v213 offset:32768
	ds_read_b128 v[4:7], v213 offset:37120
	s_waitcnt lgkmcnt(1)
	v_mfma_f32_16x16x32_bf16 v[0:3], v[0:3], v[80:83], 0
	ds_read_b128 v[8:11], v213 offset:32832
	ds_read_b128 v[12:15], v213 offset:37184
	v_pk_fma_f32 v[32:33], v[174:175], v[132:133], v[32:33]
	v_pk_fma_f32 v[48:49], v[178:179], v[136:137], v[48:49]
	s_waitcnt lgkmcnt(1)
	v_mfma_f32_16x16x32_bf16 v[0:3], v[8:11], v[84:87], v[0:3]
	ds_read_b128 v[8:11], v213 offset:32896
	ds_read_b128 v[16:19], v213 offset:37248
	v_pk_fma_f32 v[32:33], v[170:171], v[130:131], v[32:33]
	v_pk_fma_f32 v[48:49], v[168:169], v[134:135], v[48:49]
	s_waitcnt lgkmcnt(1)
	v_mfma_f32_16x16x32_bf16 v[0:3], v[8:11], v[88:91], v[0:3]
	ds_read_b128 v[8:11], v213 offset:32960
	ds_read_b128 v[20:23], v213 offset:37312
	s_waitcnt lgkmcnt(1)
	v_mfma_f32_16x16x32_bf16 v[0:3], v[8:11], v[92:95], v[0:3]
	ds_read_u16 v8, v214
	ds_read_u16 v9, v214 offset:32
	s_waitcnt lgkmcnt(1)
	v_lshlrev_b32_e32 v8, 16, v8
	s_waitcnt lgkmcnt(0)
	v_lshlrev_b32_e32 v9, 16, v9
	s_nop 1
	v_pk_fma_f32 v[0:1], v[176:177], v[8:9], v[0:1]
	v_mfma_f32_16x16x32_bf16 v[4:7], v[4:7], v[80:83], 0
	v_mul_f32_e64 v8, v0, v0
	v_mul_f32_e64 v9, v1, v1
	v_pk_fma_f32 v[8:9], v[8:9], s[20:21], v[128:129] op_sel_hi:[1,0,0] neg_lo:[1,0,0] neg_hi:[1,0,0]
	v_mfma_f32_16x16x32_bf16 v[4:7], v[12:15], v[84:87], v[4:7]
	v_mul_f32_e64 v8, v0, v8
	v_mul_f32_e64 v9, v1, v9
	v_exp_f32_e32 v8, v8
	v_exp_f32_e32 v9, v9
	v_mfma_f32_16x16x32_bf16 v[4:7], v[16:19], v[88:91], v[4:7]
	v_add_f32_e64 v8, v8, 1.0
	v_add_f32_e64 v9, v9, 1.0
	v_rcp_f32_e32 v8, v8
	v_rcp_f32_e32 v9, v9
	v_mfma_f32_16x16x32_bf16 v[4:7], v[20:23], v[92:95], v[4:7]
	v_mul_f32_e64 v0, v0, v8
	v_mul_f32_e64 v1, v1, v9
	v_cvt_pk_bf16_f32 v0, v0, v1
	ds_read_u16 v8, v214 offset:128
	ds_read_u16 v9, v214 offset:160
	ds_write_b16 v215, v0
	ds_write_b16_d16_hi v215, v0 offset:32
	ds_read_u16 v0, v214 offset:64
	ds_read_u16 v1, v214 offset:96
	ds_read_u16 v10, v214 offset:192
	ds_read_u16 v11, v214 offset:224
	v_mfma_f32_32x32x16_bf16 v[16:31], v[120:123], v[72:75], 0
	s_waitcnt lgkmcnt(3)
	v_lshlrev_b32_e32 v0, 16, v0
	s_waitcnt lgkmcnt(2)
	v_lshlrev_b32_e32 v1, 16, v1
	v_fma_f32 v0, v176, v0, v2
	v_fma_f32 v1, v177, v1, v3
	v_pk_mul_f32 v[2:3], v[0:1], v[0:1]
	s_nop 4
	v_pk_fma_f32 v[16:17], v[172:173], v[134:135], v[16:17]
	v_pk_fma_f32 v[2:3], v[2:3], s[20:21], v[128:129] op_sel_hi:[1,0,0] neg_lo:[1,0,0] neg_hi:[1,0,0]
	v_pk_fma_f32 v[16:17], v[168:169], v[136:137], v[16:17]
	v_pk_mul_f32 v[2:3], v[0:1], v[2:3]
	v_pk_fma_f32 v[50:51], v[178:179], v[16:17], v[50:51]
	v_exp_f32_e32 v2, v2
	v_exp_f32_e32 v3, v3
	v_pk_fma_f32 v[18:19], v[172:173], v[48:49], v[18:19]
	v_pk_fma_f32 v[50:51], v[168:169], v[48:49], v[50:51]
	v_pk_add_f32 v[2:3], v[2:3], 1.0 op_sel_hi:[1,0]
	s_nop 0
	v_rcp_f32_e32 v2, v2
	v_rcp_f32_e32 v3, v3
	v_pk_fma_f32 v[20:21], v[172:173], v[50:51], v[20:21]
	v_pk_mul_f32 v[0:1], v[0:1], v[2:3]
	s_nop 0
	v_cvt_pk_bf16_f32 v0, v0, v1
	ds_write_b16 v215, v0 offset:64
	ds_write_b16_d16_hi v215, v0 offset:96
	v_lshlrev_b32_e32 v1, 16, v9
	v_lshlrev_b32_e32 v0, 16, v8
	v_pk_fma_f32 v[0:1], v[176:177], v[0:1], v[4:5]
	v_add_u32_e32 v4, v138, v148
	v_pk_mul_f32 v[2:3], v[0:1], v[0:1]
	v_ashrrev_i32_e32 v5, 31, v4
	v_pk_fma_f32 v[2:3], v[2:3], s[20:21], v[128:129] op_sel_hi:[1,0,0] neg_lo:[1,0,0] neg_hi:[1,0,0]
	v_lshlrev_b64 v[4:5], 11, v[4:5]
	v_pk_mul_f32 v[2:3], v[0:1], v[2:3]
	v_lshl_add_u64 v[4:5], v[126:127], 0, v[4:5]
	v_exp_f32_e32 v2, v2
	v_exp_f32_e32 v3, v3
	s_nop 0
	v_pk_add_f32 v[2:3], v[2:3], 1.0 op_sel_hi:[1,0]
	s_nop 0
	v_rcp_f32_e32 v2, v2
	v_rcp_f32_e32 v3, v3
	s_nop 0
	v_pk_mul_f32 v[0:1], v[0:1], v[2:3]
	s_nop 0
	v_cvt_pk_bf16_f32 v0, v0, v1
	ds_write_b16 v215, v0 offset:512
	ds_write_b16_d16_hi v215, v0 offset:544
	s_waitcnt lgkmcnt(4)
	v_lshlrev_b32_e32 v1, 16, v11
	v_lshlrev_b32_e32 v0, 16, v10
	v_pk_fma_f32 v[0:1], v[176:177], v[0:1], v[6:7]
	s_nop 0
	v_pk_mul_f32 v[2:3], v[0:1], v[0:1]
	s_nop 0
	v_pk_fma_f32 v[2:3], v[2:3], s[20:21], v[128:129] op_sel_hi:[1,0,0] neg_lo:[1,0,0] neg_hi:[1,0,0]
	s_nop 0
	v_pk_mul_f32 v[2:3], v[0:1], v[2:3]
	s_nop 0
	v_exp_f32_e32 v2, v2
	v_exp_f32_e32 v3, v3
	s_nop 0
	v_pk_add_f32 v[2:3], v[2:3], 1.0 op_sel_hi:[1,0]
	s_nop 0
	v_rcp_f32_e32 v2, v2
	v_rcp_f32_e32 v3, v3
	s_nop 0
	v_pk_mul_f32 v[0:1], v[0:1], v[2:3]
	s_nop 0
	v_cvt_pk_bf16_f32 v0, v0, v1
	ds_write_b16 v215, v0 offset:576
	ds_write_b16_d16_hi v215, v0 offset:608
	s_waitcnt lgkmcnt(0)
	ds_read_b128 v[0:3], v147
	s_waitcnt lgkmcnt(0)
	global_store_dwordx4 v[4:5], v[0:3], off
	s_nop 1
	v_mfma_f32_32x32x16_bf16 v[0:15], v[120:123], v[68:71], 0
	s_waitcnt lgkmcnt(0)
; #define LAS __attribute__((address_space(3)))
; #define LDS_WAIT() asm volatile("s_waitcnt lgkmcnt(0)" ::: "memory")
; __device__ __forceinline__ unsigned cvt2(float lo, float hi) { const f2_t v = {lo, hi}; return __builtin_bit_cast(unsigned, __builtin_convertvector(v, bf2_t)); }
; __device__ __forceinline__ f2v fma2(f2v a, f2v b, f2v c) { return __builtin_elementwise_fma(a, b, c); }
; __device__ __forceinline__ void ssm_phase(Frame& F) {
;     ...
; #pragma unroll
;             for (int s = 0; s < 8; ++s) {
;                 *(LAS bf16x8*)(ut + l31 * 32 + 16 * h) = afr[s];
;                 const f32x16 D0 = __builtin_amdgcn_mfma_f32_32x32x16_bf16(afr[s], bfrag[0], z, 0, 0, 0), D1 = __builtin_amdgcn_mfma_f32_32x32x16_bf16(afr[s], bfrag[1], z, 0, 0, 0),
;                              D2 = __builtin_amdgcn_mfma_f32_32x32x16_bf16(afr[s], bfrag[2], z, 0, 0, 0), D3 = __builtin_amdgcn_mfma_f32_32x32x16_bf16(afr[s], bfrag[3], z, 0, 0, 0);
; #pragma unroll
;                 for (int t = 0; t < 8; ++t) {
;                     const f2v d0 = {D0[2 * t], D0[2 * t + 1]}, d1 = {D1[2 * t], D1[2 * t + 1]}, d2 = {D2[2 * t], D2[2 * t + 1]}, d3 = {D3[2 * t], D3[2 * t + 1]};
;                     const f2v nr0 = fma2(AR0, Sre0, fma2(NAI0, Sim0, d0)), ni0 = fma2(AR0, Sim0, fma2(AI0, Sre0, d2));
;                     const f2v nr1 = fma2(AR1, Sre1, fma2(NAI1, Sim1, d1)), ni1 = fma2(AR1, Sim1, fma2(AI1, Sre1, d3));
;                     Sre0 = nr0; Sim0 = ni0; Sre1 = nr1; Sim1 = ni1;
; #pragma unroll
;                     for (int e = 0; e < 2; ++e) { v2u w; w.x = cvt2(nr0[e], nr1[e]); w.y = cvt2(ni0[e], ni1[e]); *(LAS v2u*)(st + (16 * h + 2 * t + e) * 272 + 8 * l31) = w; }
;                 }
;                 LDS_WAIT(); asm volatile("" ::: "memory");
;                 f32x4 acc0 = (f32x4){0.f, 0.f, 0.f, 0.f}, acc1 = (f32x4){0.f, 0.f, 0.f, 0.f};
; #pragma unroll
;                 for (int ks = 0; ks < 4; ++ks) {
;                     const bf16x8 s0 = *(const LAS bf16x8*)(st + l15 * 272 + 64 * ks + 16 * qq), s1 = *(const LAS bf16x8*)(st + (16 + l15) * 272 + 64 * ks + 16 * qq);
;                     acc0 = __builtin_amdgcn_mfma_f32_16x16x32_bf16(s0, cfrag[ks], acc0, 0, 0, 0); acc1 = __builtin_amdgcn_mfma_f32_16x16x32_bf16(s1, cfrag[ks], acc1, 0, 0, 0); }
	ds_write_b128 v212, v[120:123]
	v_cvt_pk_bf16_f32 v121, v16, v32
	v_cvt_pk_bf16_f32 v123, v17, v33
	v_fma_f32 v16, v168, v16, v18
	v_fma_f32 v17, v169, v17, v19
	s_nop 6
	v_pk_fma_f32 v[0:1], v[180:181], v[130:131], v[0:1]
	s_nop 0
	v_pk_fma_f32 v[0:1], v[170:171], v[132:133], v[0:1]
	v_pk_fma_f32 v[2:3], v[180:181], v[32:33], v[2:3]
	v_cvt_pk_bf16_f32 v120, v48, v0
	v_cvt_pk_bf16_f32 v122, v49, v1
	v_pk_fma_f32 v[2:3], v[170:171], v[0:1], v[2:3]
	v_pk_fma_f32 v[0:1], v[174:175], v[0:1], v[34:35]
	v_cvt_pk_bf16_f32 v18, v50, v2
	v_pk_fma_f32 v[0:1], v[170:171], v[32:33], v[0:1]
	v_cvt_pk_bf16_f32 v32, v51, v3
	v_cvt_pk_bf16_f32 v19, v16, v0
	v_cvt_pk_bf16_f32 v33, v17, v1
	v_pk_fma_f32 v[4:5], v[180:181], v[0:1], v[4:5]
	ds_write2_b64 v149, v[18:19], v[32:33] offset0:68 offset1:102
	v_pk_fma_f32 v[18:19], v[178:179], v[16:17], v[52:53]
	v_pk_fma_f32 v[4:5], v[170:171], v[2:3], v[4:5]
	v_pk_fma_f32 v[2:3], v[174:175], v[2:3], v[36:37]
	v_pk_fma_f32 v[18:19], v[168:169], v[50:51], v[18:19]
	v_pk_fma_f32 v[16:17], v[168:169], v[16:17], v[20:21]
	v_pk_fma_f32 v[0:1], v[170:171], v[0:1], v[2:3]
	v_cvt_pk_bf16_f32 v2, v18, v4
	v_cvt_pk_bf16_f32 v3, v16, v0
	v_cvt_pk_bf16_f32 v20, v19, v5
	v_cvt_pk_bf16_f32 v21, v17, v1
	ds_write2_b64 v149, v[2:3], v[20:21] offset0:136 offset1:170
	v_pk_fma_f32 v[2:3], v[178:179], v[16:17], v[54:55]
	v_pk_fma_f32 v[6:7], v[180:181], v[0:1], v[6:7]
	v_pk_fma_f32 v[2:3], v[168:169], v[18:19], v[2:3]
	v_pk_fma_f32 v[18:19], v[172:173], v[18:19], v[22:23]
	v_pk_fma_f32 v[6:7], v[170:171], v[4:5], v[6:7]
	v_pk_fma_f32 v[4:5], v[174:175], v[4:5], v[38:39]
	v_pk_fma_f32 v[16:17], v[168:169], v[16:17], v[18:19]
	v_pk_fma_f32 v[0:1], v[170:171], v[0:1], v[4:5]
	v_cvt_pk_bf16_f32 v4, v2, v6
	v_cvt_pk_bf16_f32 v5, v16, v0
	v_cvt_pk_bf16_f32 v18, v3, v7
	v_cvt_pk_bf16_f32 v19, v17, v1
	ds_write2_b64 v149, v[4:5], v[18:19] offset0:204 offset1:238
	v_pk_fma_f32 v[4:5], v[178:179], v[16:17], v[56:57]
	v_pk_fma_f32 v[8:9], v[180:181], v[0:1], v[8:9]
	v_pk_fma_f32 v[4:5], v[168:169], v[2:3], v[4:5]
	v_pk_fma_f32 v[2:3], v[172:173], v[2:3], v[24:25]
	v_pk_fma_f32 v[8:9], v[170:171], v[6:7], v[8:9]
	v_pk_fma_f32 v[6:7], v[174:175], v[6:7], v[40:41]
	v_pk_fma_f32 v[2:3], v[168:169], v[16:17], v[2:3]
	v_pk_fma_f32 v[0:1], v[170:171], v[0:1], v[6:7]
	v_cvt_pk_bf16_f32 v6, v4, v8
	v_cvt_pk_bf16_f32 v7, v2, v0
	v_cvt_pk_bf16_f32 v16, v5, v9
	v_cvt_pk_bf16_f32 v17, v3, v1
	ds_write2_b64 v146, v[6:7], v[16:17] offset0:16 offset1:50
	v_pk_fma_f32 v[6:7], v[178:179], v[2:3], v[58:59]
	ds_write2_b64 v149, v[120:121], v[122:123] offset1:34
	v_pk_fma_f32 v[6:7], v[168:169], v[4:5], v[6:7]
	v_pk_fma_f32 v[4:5], v[172:173], v[4:5], v[26:27]
	s_nop 0
	v_pk_fma_f32 v[2:3], v[168:169], v[2:3], v[4:5]
	v_pk_fma_f32 v[4:5], v[180:181], v[0:1], v[10:11]
	s_nop 0
	v_pk_fma_f32 v[4:5], v[170:171], v[8:9], v[4:5]
	v_pk_fma_f32 v[8:9], v[174:175], v[8:9], v[42:43]
	v_cvt_pk_bf16_f32 v10, v7, v5
	v_pk_fma_f32 v[0:1], v[170:171], v[0:1], v[8:9]
	v_cvt_pk_bf16_f32 v8, v6, v4
	v_cvt_pk_bf16_f32 v9, v2, v0
	v_cvt_pk_bf16_f32 v11, v3, v1
	ds_write2_b64 v146, v[8:9], v[10:11] offset0:84 offset1:118
	v_pk_fma_f32 v[8:9], v[178:179], v[2:3], v[60:61]
	s_nop 0
	v_pk_fma_f32 v[8:9], v[168:169], v[6:7], v[8:9]
	v_pk_fma_f32 v[6:7], v[172:173], v[6:7], v[28:29]
	s_nop 0
	v_pk_fma_f32 v[2:3], v[168:169], v[2:3], v[6:7]
	v_pk_fma_f32 v[6:7], v[180:181], v[0:1], v[12:13]
	s_nop 0
	v_pk_fma_f32 v[6:7], v[170:171], v[4:5], v[6:7]
	v_pk_fma_f32 v[4:5], v[174:175], v[4:5], v[44:45]
	v_cvt_pk_bf16_f32 v10, v9, v7
	v_pk_fma_f32 v[0:1], v[170:171], v[0:1], v[4:5]
	v_cvt_pk_bf16_f32 v4, v8, v6
	v_cvt_pk_bf16_f32 v5, v2, v0
	v_cvt_pk_bf16_f32 v11, v3, v1
	ds_write2_b64 v146, v[4:5], v[10:11] offset0:152 offset1:186
	v_pk_fma_f32 v[4:5], v[178:179], v[2:3], v[62:63]
	s_waitcnt vmcnt(6)
	v_mfma_f32_32x32x16_bf16 v[48:63], v[116:119], v[72:75], 0
	v_fma_f32 v120, v168, v8, v4
	v_fma_f32 v121, v169, v9, v5
	v_fma_f32 v4, v172, v8, v30
	v_fma_f32 v5, v173, v9, v31
	v_fma_f32 v130, v168, v2, v4
	v_fma_f32 v131, v169, v3, v5
	v_pk_fma_f32 v[2:3], v[180:181], v[0:1], v[14:15]
	s_nop 4
	v_pk_fma_f32 v[48:49], v[172:173], v[120:121], v[48:49]
	v_pk_fma_f32 v[122:123], v[170:171], v[6:7], v[2:3]
	v_pk_fma_f32 v[2:3], v[174:175], v[6:7], v[46:47]
	v_mfma_f32_32x32x16_bf16 v[32:47], v[116:119], v[64:67], 0
	v_fma_f32 v132, v170, v0, v2
	v_fma_f32 v133, v171, v1, v3
	v_cvt_pk_bf16_f32 v0, v120, v122
	v_cvt_pk_bf16_f32 v1, v130, v132
	v_cvt_pk_bf16_f32 v2, v121, v123
	v_cvt_pk_bf16_f32 v3, v131, v133
	ds_write2_b64 v146, v[0:1], v[2:3] offset0:220 offset1:254
	s_waitcnt lgkmcnt(0)
	ds_read_b128 v[0:3], v213 offset:32768
	ds_read_b128 v[4:7], v213 offset:37120
	s_waitcnt lgkmcnt(1)
	v_mfma_f32_16x16x32_bf16 v[0:3], v[0:3], v[80:83], 0
	ds_read_b128 v[8:11], v213 offset:32832
	ds_read_b128 v[12:15], v213 offset:37184
	v_pk_fma_f32 v[32:33], v[178:179], v[130:131], v[32:33]
	v_pk_fma_f32 v[48:49], v[168:169], v[130:131], v[48:49]
	s_waitcnt lgkmcnt(1)
	v_mfma_f32_16x16x32_bf16 v[0:3], v[8:11], v[84:87], v[0:3]
	ds_read_b128 v[8:11], v213 offset:32896
	ds_read_b128 v[16:19], v213 offset:37248
	v_pk_fma_f32 v[32:33], v[168:169], v[120:121], v[32:33]
	v_pk_fma_f32 v[34:35], v[178:179], v[48:49], v[34:35]
	s_waitcnt lgkmcnt(1)
	v_mfma_f32_16x16x32_bf16 v[0:3], v[8:11], v[88:91], v[0:3]
	ds_read_b128 v[8:11], v213 offset:32960
	ds_read_b128 v[20:23], v213 offset:37312
	v_pk_fma_f32 v[34:35], v[168:169], v[32:33], v[34:35]
	s_waitcnt lgkmcnt(1)
	v_mfma_f32_16x16x32_bf16 v[0:3], v[8:11], v[92:95], v[0:3]
	ds_read_u16 v8, v214
	ds_read_u16 v9, v214 offset:32
	s_waitcnt lgkmcnt(1)
; #define GAS __attribute__((address_space(1)))
; __device__ __forceinline__ void ssm_phase(Frame& F) {
;     ...
; #pragma unroll
;             for (int s = 0; s < 8; ++s) {
;                 *(LAS bf16x8*)(ut + l31 * 32 + 16 * h) = afr[s];
;                 const f32x16 D0 = __builtin_amdgcn_mfma_f32_32x32x16_bf16(afr[s], bfrag[0], z, 0, 0, 0), D1 = __builtin_amdgcn_mfma_f32_32x32x16_bf16(afr[s], bfrag[1], z, 0, 0, 0),
;                              D2 = __builtin_amdgcn_mfma_f32_32x32x16_bf16(afr[s], bfrag[2], z, 0, 0, 0), D3 = __builtin_amdgcn_mfma_f32_32x32x16_bf16(afr[s], bfrag[3], z, 0, 0, 0);
; #pragma unroll
;                 for (int t = 0; t < 8; ++t) {
;                     const f2v d0 = {D0[2 * t], D0[2 * t + 1]}, d1 = {D1[2 * t], D1[2 * t + 1]}, d2 = {D2[2 * t], D2[2 * t + 1]}, d3 = {D3[2 * t], D3[2 * t + 1]};
;                     const f2v nr0 = fma2(AR0, Sre0, fma2(NAI0, Sim0, d0)), ni0 = fma2(AR0, Sim0, fma2(AI0, Sre0, d2));
;     ...
;                     acc0 = __builtin_amdgcn_mfma_f32_16x16x32_bf16(s0, cfrag[ks], acc0, 0, 0, 0); acc1 = __builtin_amdgcn_mfma_f32_16x16x32_bf16(s1, cfrag[ks], acc1, 0, 0, 0); }
;                 float uu[2][4];
; #pragma unroll
;                 for (int rb = 0; rb < 2; ++rb)
; #pragma unroll
;                     for (int i2 = 0; i2 < 4; ++i2) uu[rb][i2] = bf1(*(const LAS bf16*)(ut + (i2 + 4 * rb + 8 * qq) * 32 + 2 * l15));
; #pragma unroll
;                 for (int rb = 0; rb < 2; ++rb)
; #pragma unroll
;                     for (int i2 = 0; i2 < 4; i2 += 2) {
;                         f2v y; y.x = (rb == 0 ? acc0[i2] : acc1[i2]) + dsk * uu[rb][i2]; y.y = (rb == 0 ? acc0[i2 + 1] : acc1[i2 + 1]) + dsk * uu[rb][i2 + 1];
;                         const f2v gq = gelu_tanh2(y); const unsigned w = cvt2(gq.x, gq.y);
;                         *(LAS bf16*)(yt + (16 * rb + 4 * qq + i2) * 32 + 2 * l15) = (bf16)(w & 0xffffu); *(LAS bf16*)(yt + (16 * rb + 4 * qq + i2 + 1) * 32 + 2 * l15) = (bf16)(w >> 16); }
;                 LDS_WAIT(); asm volatile("" ::: "memory");
;                 { const int R = lane >> 1, hf = lane & 1; const v4u yv = *(const LAS v4u*)(yt + lane * 16);
;                   const int chunk = F.wave + 8 * (2 * (R >> 4) + (R & 1)) + 32 * it, tok = 8 * s + ((R & 15) >> 1);
;                   *(GAS v4u*)(gb + ((size_t)(b * SEQ + chunk * 64 + tok)) * SW + g * SG + 8 * hf) = yv; }
	v_lshlrev_b32_e32 v8, 16, v8
	s_waitcnt lgkmcnt(0)
	v_lshlrev_b32_e32 v9, 16, v9
	s_nop 1
	v_pk_fma_f32 v[0:1], v[176:177], v[8:9], v[0:1]
	v_mfma_f32_16x16x32_bf16 v[4:7], v[4:7], v[80:83], 0
	v_mul_f32_e64 v8, v0, v0
	v_mul_f32_e64 v9, v1, v1
	v_pk_fma_f32 v[8:9], v[8:9], s[20:21], v[128:129] op_sel_hi:[1,0,0] neg_lo:[1,0,0] neg_hi:[1,0,0]
	v_mfma_f32_16x16x32_bf16 v[4:7], v[12:15], v[84:87], v[4:7]
	v_mul_f32_e64 v8, v0, v8
	v_mul_f32_e64 v9, v1, v9
	v_exp_f32_e32 v8, v8
	v_exp_f32_e32 v9, v9
	v_mfma_f32_16x16x32_bf16 v[4:7], v[16:19], v[88:91], v[4:7]
	v_add_f32_e64 v8, v8, 1.0
	v_add_f32_e64 v9, v9, 1.0
	v_rcp_f32_e32 v8, v8
	v_rcp_f32_e32 v9, v9
	v_mfma_f32_16x16x32_bf16 v[4:7], v[20:23], v[92:95], v[4:7]
	v_mul_f32_e64 v0, v0, v8
	v_mul_f32_e64 v1, v1, v9
	v_cvt_pk_bf16_f32 v0, v0, v1
	ds_read_u16 v8, v214 offset:128
	ds_read_u16 v9, v214 offset:160
	ds_write_b16 v215, v0
	ds_write_b16_d16_hi v215, v0 offset:32
	ds_read_u16 v0, v214 offset:64
	ds_read_u16 v1, v214 offset:96
	ds_read_u16 v10, v214 offset:192
	ds_read_u16 v11, v214 offset:224
	v_mfma_f32_32x32x16_bf16 v[16:31], v[116:119], v[76:79], 0
	s_waitcnt lgkmcnt(3)
	v_lshlrev_b32_e32 v0, 16, v0
	s_waitcnt lgkmcnt(2)
	v_lshlrev_b32_e32 v1, 16, v1
	v_fma_f32 v0, v176, v0, v2
	v_fma_f32 v1, v177, v1, v3
	v_pk_mul_f32 v[2:3], v[0:1], v[0:1]
	s_nop 4
	v_pk_fma_f32 v[16:17], v[174:175], v[122:123], v[16:17]
	v_pk_fma_f32 v[2:3], v[2:3], s[20:21], v[128:129] op_sel_hi:[1,0,0] neg_lo:[1,0,0] neg_hi:[1,0,0]
	v_pk_fma_f32 v[16:17], v[170:171], v[132:133], v[16:17]
	v_pk_mul_f32 v[2:3], v[0:1], v[2:3]
	s_nop 0
	v_exp_f32_e32 v2, v2
	v_exp_f32_e32 v3, v3
	s_nop 0
	v_pk_add_f32 v[2:3], v[2:3], 1.0 op_sel_hi:[1,0]
	s_nop 0
	v_rcp_f32_e32 v2, v2
	v_rcp_f32_e32 v3, v3
	s_nop 0
	v_pk_mul_f32 v[0:1], v[0:1], v[2:3]
	s_nop 0
	v_cvt_pk_bf16_f32 v0, v0, v1
	ds_write_b16 v215, v0 offset:64
	ds_write_b16_d16_hi v215, v0 offset:96
	v_lshlrev_b32_e32 v1, 16, v9
	v_lshlrev_b32_e32 v0, 16, v8
	v_pk_fma_f32 v[0:1], v[176:177], v[0:1], v[4:5]
	v_add_u32_e32 v4, v139, v148
	v_pk_mul_f32 v[2:3], v[0:1], v[0:1]
	v_ashrrev_i32_e32 v5, 31, v4
	v_pk_fma_f32 v[2:3], v[2:3], s[20:21], v[128:129] op_sel_hi:[1,0,0] neg_lo:[1,0,0] neg_hi:[1,0,0]
	v_lshlrev_b64 v[4:5], 11, v[4:5]
	v_pk_mul_f32 v[2:3], v[0:1], v[2:3]
	v_lshl_add_u64 v[4:5], v[126:127], 0, v[4:5]
	v_exp_f32_e32 v2, v2
	v_exp_f32_e32 v3, v3
	s_nop 0
	v_pk_add_f32 v[2:3], v[2:3], 1.0 op_sel_hi:[1,0]
	s_nop 0
	v_rcp_f32_e32 v2, v2
	v_rcp_f32_e32 v3, v3
	s_nop 0
	v_pk_mul_f32 v[0:1], v[0:1], v[2:3]
	s_nop 0
	v_cvt_pk_bf16_f32 v0, v0, v1
	ds_write_b16 v215, v0 offset:512
	ds_write_b16_d16_hi v215, v0 offset:544
	s_waitcnt lgkmcnt(4)
	v_lshlrev_b32_e32 v1, 16, v11
	v_lshlrev_b32_e32 v0, 16, v10
	v_pk_fma_f32 v[0:1], v[176:177], v[0:1], v[6:7]
	s_nop 0
	v_pk_mul_f32 v[2:3], v[0:1], v[0:1]
	s_nop 0
	v_pk_fma_f32 v[2:3], v[2:3], s[20:21], v[128:129] op_sel_hi:[1,0,0] neg_lo:[1,0,0] neg_hi:[1,0,0]
	s_nop 0
	v_pk_mul_f32 v[2:3], v[0:1], v[2:3]
	s_nop 0
	v_exp_f32_e32 v2, v2
	v_exp_f32_e32 v3, v3
	s_nop 0
	v_pk_add_f32 v[2:3], v[2:3], 1.0 op_sel_hi:[1,0]
	s_nop 0
	v_rcp_f32_e32 v2, v2
	v_rcp_f32_e32 v3, v3
	s_nop 0
	v_pk_mul_f32 v[0:1], v[0:1], v[2:3]
	s_nop 0
	v_cvt_pk_bf16_f32 v0, v0, v1
	ds_write_b16 v215, v0 offset:576
	ds_write_b16_d16_hi v215, v0 offset:608
	s_waitcnt lgkmcnt(0)
	ds_read_b128 v[0:3], v147
	s_waitcnt lgkmcnt(0)
	global_store_dwordx4 v[4:5], v[0:3], off
	s_nop 1
	v_mfma_f32_32x32x16_bf16 v[0:15], v[116:119], v[68:71], 0
	s_waitcnt lgkmcnt(0)
	ds_write_b128 v212, v[116:119]
	v_cvt_pk_bf16_f32 v117, v48, v16
	v_cvt_pk_bf16_f32 v119, v49, v17
	s_nop 8
	v_pk_fma_f32 v[0:1], v[180:181], v[132:133], v[0:1]
	s_nop 0
	v_pk_fma_f32 v[0:1], v[170:171], v[122:123], v[0:1]
	v_pk_fma_f32 v[2:3], v[180:181], v[16:17], v[2:3]
	v_cvt_pk_bf16_f32 v116, v32, v0
	v_cvt_pk_bf16_f32 v118, v33, v1
	v_pk_fma_f32 v[32:33], v[172:173], v[32:33], v[50:51]
	v_pk_fma_f32 v[2:3], v[170:171], v[0:1], v[2:3]
	v_pk_fma_f32 v[0:1], v[174:175], v[0:1], v[18:19]
	v_pk_fma_f32 v[32:33], v[168:169], v[48:49], v[32:33]
	v_pk_fma_f32 v[0:1], v[170:171], v[16:17], v[0:1]
	v_cvt_pk_bf16_f32 v16, v34, v2
	v_cvt_pk_bf16_f32 v17, v32, v0
	v_cvt_pk_bf16_f32 v18, v35, v3
	v_cvt_pk_bf16_f32 v19, v33, v1
	v_pk_fma_f32 v[4:5], v[180:181], v[0:1], v[4:5]
	ds_write2_b64 v149, v[16:17], v[18:19] offset0:68 offset1:102
	v_pk_fma_f32 v[16:17], v[178:179], v[32:33], v[36:37]
	v_pk_fma_f32 v[18:19], v[172:173], v[34:35], v[52:53]
	v_pk_fma_f32 v[4:5], v[170:171], v[2:3], v[4:5]
	v_pk_fma_f32 v[2:3], v[174:175], v[2:3], v[20:21]
	v_pk_fma_f32 v[16:17], v[168:169], v[34:35], v[16:17]
	v_pk_fma_f32 v[18:19], v[168:169], v[32:33], v[18:19]
	v_pk_fma_f32 v[0:1], v[170:171], v[0:1], v[2:3]
	v_cvt_pk_bf16_f32 v2, v16, v4
	v_cvt_pk_bf16_f32 v3, v18, v0
	v_cvt_pk_bf16_f32 v20, v17, v5
	v_cvt_pk_bf16_f32 v21, v19, v1
	ds_write2_b64 v149, v[2:3], v[20:21] offset0:136 offset1:170
	v_pk_fma_f32 v[2:3], v[178:179], v[18:19], v[38:39]
	v_pk_fma_f32 v[6:7], v[180:181], v[0:1], v[6:7]
	v_pk_fma_f32 v[2:3], v[168:169], v[16:17], v[2:3]
	v_pk_fma_f32 v[16:17], v[172:173], v[16:17], v[54:55]
	v_pk_fma_f32 v[6:7], v[170:171], v[4:5], v[6:7]
	v_pk_fma_f32 v[4:5], v[174:175], v[4:5], v[22:23]
	v_pk_fma_f32 v[16:17], v[168:169], v[18:19], v[16:17]
	v_pk_fma_f32 v[0:1], v[170:171], v[0:1], v[4:5]
	v_cvt_pk_bf16_f32 v4, v2, v6
	v_cvt_pk_bf16_f32 v5, v16, v0
	v_cvt_pk_bf16_f32 v18, v3, v7
	v_cvt_pk_bf16_f32 v19, v17, v1
	ds_write2_b64 v149, v[4:5], v[18:19] offset0:204 offset1:238
	v_pk_fma_f32 v[4:5], v[178:179], v[16:17], v[40:41]
	v_pk_fma_f32 v[8:9], v[180:181], v[0:1], v[8:9]
	v_pk_fma_f32 v[4:5], v[168:169], v[2:3], v[4:5]
; #define LAS __attribute__((address_space(3)))
; #define LDS_WAIT() asm volatile("s_waitcnt lgkmcnt(0)" ::: "memory")
; __device__ __forceinline__ void ssm_phase(Frame& F) {
;     ...
; #pragma unroll
;             for (int s = 0; s < 8; ++s) {
;                 *(LAS bf16x8*)(ut + l31 * 32 + 16 * h) = afr[s];
;                 const f32x16 D0 = __builtin_amdgcn_mfma_f32_32x32x16_bf16(afr[s], bfrag[0], z, 0, 0, 0), D1 = __builtin_amdgcn_mfma_f32_32x32x16_bf16(afr[s], bfrag[1], z, 0, 0, 0),
;                              D2 = __builtin_amdgcn_mfma_f32_32x32x16_bf16(afr[s], bfrag[2], z, 0, 0, 0), D3 = __builtin_amdgcn_mfma_f32_32x32x16_bf16(afr[s], bfrag[3], z, 0, 0, 0);
; #pragma unroll
;                 for (int t = 0; t < 8; ++t) {
;                     const f2v d0 = {D0[2 * t], D0[2 * t + 1]}, d1 = {D1[2 * t], D1[2 * t + 1]}, d2 = {D2[2 * t], D2[2 * t + 1]}, d3 = {D3[2 * t], D3[2 * t + 1]};
;                     const f2v nr0 = fma2(AR0, Sre0, fma2(NAI0, Sim0, d0)), ni0 = fma2(AR0, Sim0, fma2(AI0, Sre0, d2));
;                     const f2v nr1 = fma2(AR1, Sre1, fma2(NAI1, Sim1, d1)), ni1 = fma2(AR1, Sim1, fma2(AI1, Sre1, d3));
;                     Sre0 = nr0; Sim0 = ni0; Sre1 = nr1; Sim1 = ni1;
; #pragma unroll
;                     for (int e = 0; e < 2; ++e) { v2u w; w.x = cvt2(nr0[e], nr1[e]); w.y = cvt2(ni0[e], ni1[e]); *(LAS v2u*)(st + (16 * h + 2 * t + e) * 272 + 8 * l31) = w; }
;                 }
;                 LDS_WAIT(); asm volatile("" ::: "memory");
;                 f32x4 acc0 = (f32x4){0.f, 0.f, 0.f, 0.f}, acc1 = (f32x4){0.f, 0.f, 0.f, 0.f};
; #pragma unroll
;                 for (int ks = 0; ks < 4; ++ks) {
;                     const bf16x8 s0 = *(const LAS bf16x8*)(st + l15 * 272 + 64 * ks + 16 * qq), s1 = *(const LAS bf16x8*)(st + (16 + l15) * 272 + 64 * ks + 16 * qq);
;                     acc0 = __builtin_amdgcn_mfma_f32_16x16x32_bf16(s0, cfrag[ks], acc0, 0, 0, 0); acc1 = __builtin_amdgcn_mfma_f32_16x16x32_bf16(s1, cfrag[ks], acc1, 0, 0, 0); }
;                 float uu[2][4];
; #pragma unroll
;                 for (int rb = 0; rb < 2; ++rb)
; #pragma unroll
;                     for (int i2 = 0; i2 < 4; ++i2) uu[rb][i2] = bf1(*(const LAS bf16*)(ut + (i2 + 4 * rb + 8 * qq) * 32 + 2 * l15));
; #pragma unroll
;                 for (int rb = 0; rb < 2; ++rb)
; #pragma unroll
;                     for (int i2 = 0; i2 < 4; i2 += 2) {
	v_pk_fma_f32 v[2:3], v[172:173], v[2:3], v[56:57]
	v_pk_fma_f32 v[8:9], v[170:171], v[6:7], v[8:9]
	v_pk_fma_f32 v[6:7], v[174:175], v[6:7], v[24:25]
	v_pk_fma_f32 v[2:3], v[168:169], v[16:17], v[2:3]
	v_pk_fma_f32 v[0:1], v[170:171], v[0:1], v[6:7]
	v_cvt_pk_bf16_f32 v6, v4, v8
	v_cvt_pk_bf16_f32 v7, v2, v0
	v_cvt_pk_bf16_f32 v16, v5, v9
	v_cvt_pk_bf16_f32 v17, v3, v1
	ds_write2_b64 v146, v[6:7], v[16:17] offset0:16 offset1:50
	v_pk_fma_f32 v[6:7], v[178:179], v[2:3], v[42:43]
	ds_write2_b64 v149, v[116:117], v[118:119] offset1:34
	v_pk_fma_f32 v[6:7], v[168:169], v[4:5], v[6:7]
	v_pk_fma_f32 v[4:5], v[172:173], v[4:5], v[58:59]
	s_nop 0
	v_pk_fma_f32 v[2:3], v[168:169], v[2:3], v[4:5]
	v_pk_fma_f32 v[4:5], v[180:181], v[0:1], v[10:11]
	s_nop 0
	v_pk_fma_f32 v[4:5], v[170:171], v[8:9], v[4:5]
	v_pk_fma_f32 v[8:9], v[174:175], v[8:9], v[26:27]
	v_cvt_pk_bf16_f32 v10, v7, v5
	v_pk_fma_f32 v[0:1], v[170:171], v[0:1], v[8:9]
	v_cvt_pk_bf16_f32 v8, v6, v4
	v_cvt_pk_bf16_f32 v9, v2, v0
	v_cvt_pk_bf16_f32 v11, v3, v1
	ds_write2_b64 v146, v[8:9], v[10:11] offset0:84 offset1:118
	v_pk_fma_f32 v[8:9], v[178:179], v[2:3], v[44:45]
	s_nop 0
	v_pk_fma_f32 v[8:9], v[168:169], v[6:7], v[8:9]
	v_pk_fma_f32 v[6:7], v[172:173], v[6:7], v[60:61]
	s_nop 0
	v_pk_fma_f32 v[2:3], v[168:169], v[2:3], v[6:7]
	v_pk_fma_f32 v[6:7], v[180:181], v[0:1], v[12:13]
	s_nop 0
	v_pk_fma_f32 v[6:7], v[170:171], v[4:5], v[6:7]
	v_pk_fma_f32 v[4:5], v[174:175], v[4:5], v[28:29]
	v_cvt_pk_bf16_f32 v10, v9, v7
	v_pk_fma_f32 v[0:1], v[170:171], v[0:1], v[4:5]
	v_cvt_pk_bf16_f32 v4, v8, v6
	v_cvt_pk_bf16_f32 v5, v2, v0
	v_cvt_pk_bf16_f32 v11, v3, v1
	ds_write2_b64 v146, v[4:5], v[10:11] offset0:152 offset1:186
	v_pk_fma_f32 v[4:5], v[178:179], v[2:3], v[46:47]
	s_waitcnt vmcnt(6)
	v_mfma_f32_32x32x16_bf16 v[32:47], v[112:115], v[72:75], 0
	v_fma_f32 v116, v168, v8, v4
	v_fma_f32 v117, v169, v9, v5
	v_fma_f32 v4, v172, v8, v62
	v_fma_f32 v5, v173, v9, v63
	v_fma_f32 v120, v168, v2, v4
	v_fma_f32 v121, v169, v3, v5
	v_pk_fma_f32 v[2:3], v[180:181], v[0:1], v[14:15]
	s_nop 4
	v_pk_fma_f32 v[32:33], v[172:173], v[116:117], v[32:33]
	v_pk_fma_f32 v[118:119], v[170:171], v[6:7], v[2:3]
	v_pk_fma_f32 v[2:3], v[174:175], v[6:7], v[30:31]
	v_mfma_f32_32x32x16_bf16 v[48:63], v[112:115], v[64:67], 0
	v_fma_f32 v122, v170, v0, v2
	v_fma_f32 v123, v171, v1, v3
	v_cvt_pk_bf16_f32 v0, v116, v118
	v_cvt_pk_bf16_f32 v1, v120, v122
	v_cvt_pk_bf16_f32 v2, v117, v119
	v_cvt_pk_bf16_f32 v3, v121, v123
	ds_write2_b64 v146, v[0:1], v[2:3] offset0:220 offset1:254
	s_waitcnt lgkmcnt(0)
	ds_read_b128 v[0:3], v213 offset:32768
	ds_read_b128 v[4:7], v213 offset:37120
	s_waitcnt lgkmcnt(1)
	v_mfma_f32_16x16x32_bf16 v[0:3], v[0:3], v[80:83], 0
	ds_read_b128 v[8:11], v213 offset:32832
	ds_read_b128 v[12:15], v213 offset:37184
	v_pk_fma_f32 v[48:49], v[178:179], v[120:121], v[48:49]
	v_pk_fma_f32 v[32:33], v[168:169], v[120:121], v[32:33]
	s_waitcnt lgkmcnt(1)
	v_mfma_f32_16x16x32_bf16 v[0:3], v[8:11], v[84:87], v[0:3]
	ds_read_b128 v[8:11], v213 offset:32896
	ds_read_b128 v[16:19], v213 offset:37248
	v_pk_fma_f32 v[48:49], v[168:169], v[116:117], v[48:49]
	v_pk_fma_f32 v[50:51], v[178:179], v[32:33], v[50:51]
	s_waitcnt lgkmcnt(1)
	v_mfma_f32_16x16x32_bf16 v[0:3], v[8:11], v[88:91], v[0:3]
	ds_read_b128 v[8:11], v213 offset:32960
	ds_read_b128 v[20:23], v213 offset:37312
	v_pk_fma_f32 v[34:35], v[172:173], v[48:49], v[34:35]
	v_pk_fma_f32 v[50:51], v[168:169], v[48:49], v[50:51]
	s_waitcnt lgkmcnt(1)
	v_mfma_f32_16x16x32_bf16 v[0:3], v[8:11], v[92:95], v[0:3]
	ds_read_u16 v8, v214
	ds_read_u16 v9, v214 offset:32
	s_waitcnt lgkmcnt(1)
	v_lshlrev_b32_e32 v8, 16, v8
	s_waitcnt lgkmcnt(0)
	v_lshlrev_b32_e32 v9, 16, v9
	s_nop 1
	v_pk_fma_f32 v[0:1], v[176:177], v[8:9], v[0:1]
	v_mfma_f32_16x16x32_bf16 v[4:7], v[4:7], v[80:83], 0
	v_mul_f32_e64 v8, v0, v0
	v_mul_f32_e64 v9, v1, v1
	v_pk_fma_f32 v[8:9], v[8:9], s[20:21], v[128:129] op_sel_hi:[1,0,0] neg_lo:[1,0,0] neg_hi:[1,0,0]
	v_mfma_f32_16x16x32_bf16 v[4:7], v[12:15], v[84:87], v[4:7]
	v_mul_f32_e64 v8, v0, v8
	v_mul_f32_e64 v9, v1, v9
	v_exp_f32_e32 v8, v8
	v_exp_f32_e32 v9, v9
	v_mfma_f32_16x16x32_bf16 v[4:7], v[16:19], v[88:91], v[4:7]
	v_add_f32_e64 v8, v8, 1.0
	v_add_f32_e64 v9, v9, 1.0
	v_rcp_f32_e32 v8, v8
	v_rcp_f32_e32 v9, v9
	v_mfma_f32_16x16x32_bf16 v[4:7], v[20:23], v[92:95], v[4:7]
	v_mul_f32_e64 v0, v0, v8
	v_mul_f32_e64 v1, v1, v9
	v_cvt_pk_bf16_f32 v0, v0, v1
	ds_read_u16 v8, v214 offset:128
	ds_read_u16 v9, v214 offset:160
	ds_write_b16 v215, v0
	ds_write_b16_d16_hi v215, v0 offset:32
	ds_read_u16 v0, v214 offset:64
	ds_read_u16 v1, v214 offset:96
	ds_read_u16 v10, v214 offset:192
	ds_read_u16 v11, v214 offset:224
	v_mfma_f32_32x32x16_bf16 v[16:31], v[112:115], v[68:71], 0
	s_waitcnt lgkmcnt(3)
	v_lshlrev_b32_e32 v0, 16, v0
	s_waitcnt lgkmcnt(2)
	v_lshlrev_b32_e32 v1, 16, v1
	v_fma_f32 v0, v176, v0, v2
	v_fma_f32 v1, v177, v1, v3
	v_pk_mul_f32 v[2:3], v[0:1], v[0:1]
	s_nop 4
	v_pk_fma_f32 v[16:17], v[180:181], v[122:123], v[16:17]
	v_pk_fma_f32 v[2:3], v[2:3], s[20:21], v[128:129] op_sel_hi:[1,0,0] neg_lo:[1,0,0] neg_hi:[1,0,0]
	v_pk_fma_f32 v[16:17], v[170:171], v[118:119], v[16:17]
	v_pk_mul_f32 v[2:3], v[0:1], v[2:3]
	s_nop 0
	v_exp_f32_e32 v2, v2
	v_exp_f32_e32 v3, v3
	s_nop 0
	v_pk_add_f32 v[2:3], v[2:3], 1.0 op_sel_hi:[1,0]
	s_nop 0
	v_rcp_f32_e32 v2, v2
	v_rcp_f32_e32 v3, v3
	s_nop 0
	v_pk_mul_f32 v[0:1], v[0:1], v[2:3]
	s_nop 0
	v_cvt_pk_bf16_f32 v0, v0, v1
	ds_write_b16 v215, v0 offset:64
	ds_write_b16_d16_hi v215, v0 offset:96
	v_lshlrev_b32_e32 v1, 16, v9
	v_lshlrev_b32_e32 v0, 16, v8
	v_pk_fma_f32 v[0:1], v[176:177], v[0:1], v[4:5]
	v_add_u32_e32 v4, v140, v148
	v_pk_mul_f32 v[2:3], v[0:1], v[0:1]
	v_ashrrev_i32_e32 v5, 31, v4
	v_pk_fma_f32 v[2:3], v[2:3], s[20:21], v[128:129] op_sel_hi:[1,0,0] neg_lo:[1,0,0] neg_hi:[1,0,0]
	v_lshlrev_b64 v[4:5], 11, v[4:5]
	v_pk_mul_f32 v[2:3], v[0:1], v[2:3]
	v_lshl_add_u64 v[4:5], v[126:127], 0, v[4:5]
	v_exp_f32_e32 v2, v2
	v_exp_f32_e32 v3, v3
	s_nop 0
	v_pk_add_f32 v[2:3], v[2:3], 1.0 op_sel_hi:[1,0]
	s_nop 0
	v_rcp_f32_e32 v2, v2
	v_rcp_f32_e32 v3, v3
	s_nop 0
	v_pk_mul_f32 v[0:1], v[0:1], v[2:3]
	s_nop 0
	v_cvt_pk_bf16_f32 v0, v0, v1
	ds_write_b16 v215, v0 offset:512
	ds_write_b16_d16_hi v215, v0 offset:544
	s_waitcnt lgkmcnt(4)
; #define LAS __attribute__((address_space(3)))
; #define LDS_WAIT() asm volatile("s_waitcnt lgkmcnt(0)" ::: "memory")
; __device__ __forceinline__ void ssm_phase(Frame& F) {
;     ...
; #pragma unroll
;             for (int s = 0; s < 8; ++s) {
;                 *(LAS bf16x8*)(ut + l31 * 32 + 16 * h) = afr[s];
;                 const f32x16 D0 = __builtin_amdgcn_mfma_f32_32x32x16_bf16(afr[s], bfrag[0], z, 0, 0, 0), D1 = __builtin_amdgcn_mfma_f32_32x32x16_bf16(afr[s], bfrag[1], z, 0, 0, 0),
;                              D2 = __builtin_amdgcn_mfma_f32_32x32x16_bf16(afr[s], bfrag[2], z, 0, 0, 0), D3 = __builtin_amdgcn_mfma_f32_32x32x16_bf16(afr[s], bfrag[3], z, 0, 0, 0);
; #pragma unroll
;                 for (int t = 0; t < 8; ++t) {
;                     const f2v d0 = {D0[2 * t], D0[2 * t + 1]}, d1 = {D1[2 * t], D1[2 * t + 1]}, d2 = {D2[2 * t], D2[2 * t + 1]}, d3 = {D3[2 * t], D3[2 * t + 1]};
;                     const f2v nr0 = fma2(AR0, Sre0, fma2(NAI0, Sim0, d0)), ni0 = fma2(AR0, Sim0, fma2(AI0, Sre0, d2));
;                     const f2v nr1 = fma2(AR1, Sre1, fma2(NAI1, Sim1, d1)), ni1 = fma2(AR1, Sim1, fma2(AI1, Sre1, d3));
;                     Sre0 = nr0; Sim0 = ni0; Sre1 = nr1; Sim1 = ni1;
; #pragma unroll
;                     for (int e = 0; e < 2; ++e) { v2u w; w.x = cvt2(nr0[e], nr1[e]); w.y = cvt2(ni0[e], ni1[e]); *(LAS v2u*)(st + (16 * h + 2 * t + e) * 272 + 8 * l31) = w; }
;                 }
;                 LDS_WAIT(); asm volatile("" ::: "memory");
;                 f32x4 acc0 = (f32x4){0.f, 0.f, 0.f, 0.f}, acc1 = (f32x4){0.f, 0.f, 0.f, 0.f};
; #pragma unroll
;                 for (int ks = 0; ks < 4; ++ks) {
;                     const bf16x8 s0 = *(const LAS bf16x8*)(st + l15 * 272 + 64 * ks + 16 * qq), s1 = *(const LAS bf16x8*)(st + (16 + l15) * 272 + 64 * ks + 16 * qq);
;                     acc0 = __builtin_amdgcn_mfma_f32_16x16x32_bf16(s0, cfrag[ks], acc0, 0, 0, 0); acc1 = __builtin_amdgcn_mfma_f32_16x16x32_bf16(s1, cfrag[ks], acc1, 0, 0, 0); }
;                 float uu[2][4];
; #pragma unroll
;                 for (int rb = 0; rb < 2; ++rb)
; #pragma unroll
;                     for (int i2 = 0; i2 < 4; ++i2) uu[rb][i2] = bf1(*(const LAS bf16*)(ut + (i2 + 4 * rb + 8 * qq) * 32 + 2 * l15));
; #pragma unroll
;                 for (int rb = 0; rb < 2; ++rb)
; #pragma unroll
;                     for (int i2 = 0; i2 < 4; i2 += 2) {
	v_lshlrev_b32_e32 v1, 16, v11
	v_lshlrev_b32_e32 v0, 16, v10
	v_pk_fma_f32 v[0:1], v[176:177], v[0:1], v[6:7]
	s_nop 0
	v_pk_mul_f32 v[2:3], v[0:1], v[0:1]
	s_nop 0
	v_pk_fma_f32 v[2:3], v[2:3], s[20:21], v[128:129] op_sel_hi:[1,0,0] neg_lo:[1,0,0] neg_hi:[1,0,0]
	s_nop 0
	v_pk_mul_f32 v[2:3], v[0:1], v[2:3]
	s_nop 0
	v_exp_f32_e32 v2, v2
	v_exp_f32_e32 v3, v3
	s_nop 0
	v_pk_add_f32 v[2:3], v[2:3], 1.0 op_sel_hi:[1,0]
	s_nop 0
	v_rcp_f32_e32 v2, v2
	v_rcp_f32_e32 v3, v3
	s_nop 0
	v_pk_mul_f32 v[0:1], v[0:1], v[2:3]
	s_nop 0
	v_cvt_pk_bf16_f32 v0, v0, v1
	ds_write_b16 v215, v0 offset:576
	ds_write_b16_d16_hi v215, v0 offset:608
	s_waitcnt lgkmcnt(0)
	ds_read_b128 v[0:3], v147
	s_waitcnt lgkmcnt(0)
	global_store_dwordx4 v[4:5], v[0:3], off
	s_nop 1
	v_mfma_f32_32x32x16_bf16 v[0:15], v[112:115], v[76:79], 0
	s_waitcnt lgkmcnt(0)
	ds_write_b128 v212, v[112:115]
	v_cvt_pk_bf16_f32 v112, v48, v16
	v_cvt_pk_bf16_f32 v114, v49, v17
	s_nop 8
	v_pk_fma_f32 v[0:1], v[174:175], v[118:119], v[0:1]
	s_nop 0
	v_pk_fma_f32 v[0:1], v[170:171], v[122:123], v[0:1]
	v_pk_fma_f32 v[2:3], v[174:175], v[16:17], v[2:3]
	v_pk_fma_f32 v[18:19], v[180:181], v[0:1], v[18:19]
	v_cvt_pk_bf16_f32 v113, v32, v0
	v_cvt_pk_bf16_f32 v115, v33, v1
	v_pk_fma_f32 v[32:33], v[168:169], v[32:33], v[34:35]
	v_pk_fma_f32 v[18:19], v[170:171], v[16:17], v[18:19]
	v_pk_fma_f32 v[0:1], v[170:171], v[0:1], v[2:3]
	v_cvt_pk_bf16_f32 v2, v50, v18
	v_cvt_pk_bf16_f32 v3, v32, v0
	v_cvt_pk_bf16_f32 v16, v51, v19
	v_cvt_pk_bf16_f32 v17, v33, v1
	ds_write2_b64 v149, v[2:3], v[16:17] offset0:68 offset1:102
	v_pk_fma_f32 v[2:3], v[178:179], v[32:33], v[52:53]
	v_pk_fma_f32 v[16:17], v[172:173], v[50:51], v[36:37]
	v_pk_fma_f32 v[20:21], v[180:181], v[0:1], v[20:21]
	v_pk_fma_f32 v[4:5], v[174:175], v[18:19], v[4:5]
	v_pk_fma_f32 v[2:3], v[168:169], v[50:51], v[2:3]
	v_pk_fma_f32 v[16:17], v[168:169], v[32:33], v[16:17]
	v_pk_fma_f32 v[20:21], v[170:171], v[18:19], v[20:21]
	v_pk_fma_f32 v[0:1], v[170:171], v[0:1], v[4:5]
	v_cvt_pk_bf16_f32 v4, v2, v20
	v_cvt_pk_bf16_f32 v5, v16, v0
	v_cvt_pk_bf16_f32 v18, v3, v21
	v_cvt_pk_bf16_f32 v19, v17, v1
	ds_write2_b64 v149, v[4:5], v[18:19] offset0:136 offset1:170
	v_pk_fma_f32 v[4:5], v[178:179], v[16:17], v[54:55]
	v_pk_fma_f32 v[6:7], v[174:175], v[20:21], v[6:7]
	v_pk_fma_f32 v[4:5], v[168:169], v[2:3], v[4:5]
	v_pk_fma_f32 v[2:3], v[172:173], v[2:3], v[38:39]
	ds_write2_b64 v149, v[112:113], v[114:115] offset1:34
	v_pk_fma_f32 v[2:3], v[168:169], v[16:17], v[2:3]
	v_pk_fma_f32 v[16:17], v[180:181], v[0:1], v[22:23]
	v_pk_fma_f32 v[0:1], v[170:171], v[0:1], v[6:7]
	v_pk_fma_f32 v[16:17], v[170:171], v[20:21], v[16:17]
	v_cvt_pk_bf16_f32 v7, v2, v0
	v_cvt_pk_bf16_f32 v6, v4, v16
	v_cvt_pk_bf16_f32 v18, v5, v17
	v_cvt_pk_bf16_f32 v19, v3, v1
	ds_write2_b64 v149, v[6:7], v[18:19] offset0:204 offset1:238
	v_pk_fma_f32 v[6:7], v[178:179], v[2:3], v[56:57]
	v_pk_fma_f32 v[8:9], v[174:175], v[16:17], v[8:9]
	v_pk_fma_f32 v[6:7], v[168:169], v[4:5], v[6:7]
	v_pk_fma_f32 v[4:5], v[172:173], v[4:5], v[40:41]
	s_nop 0
	v_pk_fma_f32 v[2:3], v[168:169], v[2:3], v[4:5]
	v_pk_fma_f32 v[4:5], v[180:181], v[0:1], v[24:25]
	v_pk_fma_f32 v[0:1], v[170:171], v[0:1], v[8:9]
	v_pk_fma_f32 v[4:5], v[170:171], v[16:17], v[4:5]
	v_cvt_pk_bf16_f32 v9, v2, v0
	v_cvt_pk_bf16_f32 v8, v6, v4
	v_cvt_pk_bf16_f32 v16, v7, v5
	v_cvt_pk_bf16_f32 v17, v3, v1
	ds_write2_b64 v146, v[8:9], v[16:17] offset0:16 offset1:50
	v_pk_fma_f32 v[8:9], v[178:179], v[2:3], v[58:59]
	s_nop 0
	v_pk_fma_f32 v[8:9], v[168:169], v[6:7], v[8:9]
	v_pk_fma_f32 v[6:7], v[172:173], v[6:7], v[42:43]
	s_nop 0
	v_pk_fma_f32 v[2:3], v[168:169], v[2:3], v[6:7]
	v_pk_fma_f32 v[6:7], v[180:181], v[0:1], v[26:27]
	s_nop 0
	v_pk_fma_f32 v[16:17], v[170:171], v[4:5], v[6:7]
	v_pk_fma_f32 v[4:5], v[174:175], v[4:5], v[10:11]
	s_nop 0
	v_pk_fma_f32 v[10:11], v[170:171], v[0:1], v[4:5]
	v_cvt_pk_bf16_f32 v0, v8, v16
	v_cvt_pk_bf16_f32 v1, v2, v10
	v_cvt_pk_bf16_f32 v4, v9, v17
	v_cvt_pk_bf16_f32 v5, v3, v11
	ds_write2_b64 v146, v[0:1], v[4:5] offset0:84 offset1:118
	v_pk_fma_f32 v[0:1], v[178:179], v[2:3], v[60:61]
	s_nop 0
	v_pk_fma_f32 v[4:5], v[168:169], v[8:9], v[0:1]
	v_pk_fma_f32 v[0:1], v[172:173], v[8:9], v[44:45]
	s_nop 0
	v_pk_fma_f32 v[6:7], v[168:169], v[2:3], v[0:1]
	v_pk_fma_f32 v[0:1], v[180:181], v[10:11], v[28:29]
	v_pk_fma_f32 v[2:3], v[174:175], v[16:17], v[12:13]
	v_pk_fma_f32 v[0:1], v[170:171], v[16:17], v[0:1]
	v_pk_fma_f32 v[2:3], v[170:171], v[10:11], v[2:3]
	v_cvt_pk_bf16_f32 v8, v4, v0
	v_cvt_pk_bf16_f32 v9, v6, v2
	v_cvt_pk_bf16_f32 v10, v5, v1
	v_cvt_pk_bf16_f32 v11, v7, v3
	ds_write2_b64 v146, v[8:9], v[10:11] offset0:152 offset1:186
	v_pk_fma_f32 v[8:9], v[178:179], v[6:7], v[62:63]
	s_waitcnt vmcnt(6)
	v_mfma_f32_32x32x16_bf16 v[48:63], v[108:111], v[64:67], 0
	v_fma_f32 v112, v168, v4, v8
	v_fma_f32 v113, v169, v5, v9
	v_fma_f32 v4, v172, v4, v46
	v_fma_f32 v5, v173, v5, v47
	v_fma_f32 v114, v168, v6, v4
	v_fma_f32 v115, v169, v7, v5
	v_pk_fma_f32 v[4:5], v[180:181], v[2:3], v[30:31]
	s_nop 4
	v_pk_fma_f32 v[48:49], v[178:179], v[114:115], v[48:49]
	v_pk_fma_f32 v[116:117], v[170:171], v[0:1], v[4:5]
	v_pk_fma_f32 v[0:1], v[174:175], v[0:1], v[14:15]
	v_mfma_f32_32x32x16_bf16 v[32:47], v[108:111], v[72:75], 0
	v_fma_f32 v118, v170, v2, v0
	v_fma_f32 v119, v171, v3, v1
	v_cvt_pk_bf16_f32 v0, v112, v116
	v_cvt_pk_bf16_f32 v1, v114, v118
	v_cvt_pk_bf16_f32 v2, v113, v117
	v_cvt_pk_bf16_f32 v3, v115, v119
	ds_write2_b64 v146, v[0:1], v[2:3] offset0:220 offset1:254
	s_waitcnt lgkmcnt(0)
	ds_read_b128 v[0:3], v213 offset:32768
	ds_read_b128 v[4:7], v213 offset:37120
	s_waitcnt lgkmcnt(1)
; #define GAS __attribute__((address_space(1)))
; #define LAS __attribute__((address_space(3)))
; #define LDS_WAIT() asm volatile("s_waitcnt lgkmcnt(0)" ::: "memory")
; __device__ __forceinline__ float bf1(bf16 v) { return __uint_as_float((unsigned)v << 16); }
; __device__ __forceinline__ unsigned cvt2(float lo, float hi) { const f2_t v = {lo, hi}; return __builtin_bit_cast(unsigned, __builtin_convertvector(v, bf2_t)); }
; __device__ __forceinline__ void ssm_phase(Frame& F) {
;     ...
;                 f32x4 acc0 = (f32x4){0.f, 0.f, 0.f, 0.f}, acc1 = (f32x4){0.f, 0.f, 0.f, 0.f};
; #pragma unroll
;                 for (int ks = 0; ks < 4; ++ks) {
;                     const bf16x8 s0 = *(const LAS bf16x8*)(st + l15 * 272 + 64 * ks + 16 * qq), s1 = *(const LAS bf16x8*)(st + (16 + l15) * 272 + 64 * ks + 16 * qq);
;                     acc0 = __builtin_amdgcn_mfma_f32_16x16x32_bf16(s0, cfrag[ks], acc0, 0, 0, 0); acc1 = __builtin_amdgcn_mfma_f32_16x16x32_bf16(s1, cfrag[ks], acc1, 0, 0, 0); }
;                 float uu[2][4];
; #pragma unroll
;                 for (int rb = 0; rb < 2; ++rb)
; #pragma unroll
;                     for (int i2 = 0; i2 < 4; ++i2) uu[rb][i2] = bf1(*(const LAS bf16*)(ut + (i2 + 4 * rb + 8 * qq) * 32 + 2 * l15));
; #pragma unroll
;                 for (int rb = 0; rb < 2; ++rb)
; #pragma unroll
;                     for (int i2 = 0; i2 < 4; i2 += 2) {
;                         f2v y; y.x = (rb == 0 ? acc0[i2] : acc1[i2]) + dsk * uu[rb][i2]; y.y = (rb == 0 ? acc0[i2 + 1] : acc1[i2 + 1]) + dsk * uu[rb][i2 + 1];
;                         const f2v gq = gelu_tanh2(y); const unsigned w = cvt2(gq.x, gq.y);
;                         *(LAS bf16*)(yt + (16 * rb + 4 * qq + i2) * 32 + 2 * l15) = (bf16)(w & 0xffffu); *(LAS bf16*)(yt + (16 * rb + 4 * qq + i2 + 1) * 32 + 2 * l15) = (bf16)(w >> 16); }
;                 LDS_WAIT(); asm volatile("" ::: "memory");
;                 { const int R = lane >> 1, hf = lane & 1; const v4u yv = *(const LAS v4u*)(yt + lane * 16);
;                   const int chunk = F.wave + 8 * (2 * (R >> 4) + (R & 1)) + 32 * it, tok = 8 * s + ((R & 15) >> 1);
;                   *(GAS v4u*)(gb + ((size_t)(b * SEQ + chunk * 64 + tok)) * SW + g * SG + 8 * hf) = yv; }
	v_mfma_f32_16x16x32_bf16 v[0:3], v[0:3], v[80:83], 0
	ds_read_b128 v[8:11], v213 offset:32832
	ds_read_b128 v[12:15], v213 offset:37184
	v_pk_fma_f32 v[32:33], v[172:173], v[112:113], v[32:33]
	v_pk_fma_f32 v[48:49], v[168:169], v[112:113], v[48:49]
	s_waitcnt lgkmcnt(1)
	v_mfma_f32_16x16x32_bf16 v[0:3], v[8:11], v[84:87], v[0:3]
	ds_read_b128 v[8:11], v213 offset:32896
	ds_read_b128 v[16:19], v213 offset:37248
	v_pk_fma_f32 v[32:33], v[168:169], v[114:115], v[32:33]
	v_pk_fma_f32 v[34:35], v[172:173], v[48:49], v[34:35]
	s_waitcnt lgkmcnt(1)
	v_mfma_f32_16x16x32_bf16 v[0:3], v[8:11], v[88:91], v[0:3]
	ds_read_b128 v[8:11], v213 offset:32960
	ds_read_b128 v[20:23], v213 offset:37312
	v_pk_fma_f32 v[50:51], v[178:179], v[32:33], v[50:51]
	s_waitcnt lgkmcnt(1)
	v_mfma_f32_16x16x32_bf16 v[0:3], v[8:11], v[92:95], v[0:3]
	ds_read_u16 v8, v214
	ds_read_u16 v9, v214 offset:32
	v_pk_fma_f32 v[50:51], v[168:169], v[48:49], v[50:51]
	s_waitcnt lgkmcnt(1)
	v_lshlrev_b32_e32 v8, 16, v8
	s_waitcnt lgkmcnt(0)
	v_lshlrev_b32_e32 v9, 16, v9
	s_nop 0
	v_pk_fma_f32 v[0:1], v[176:177], v[8:9], v[0:1]
	v_mfma_f32_16x16x32_bf16 v[4:7], v[4:7], v[80:83], 0
	v_mul_f32_e64 v8, v0, v0
	v_mul_f32_e64 v9, v1, v1
	v_pk_fma_f32 v[8:9], v[8:9], s[20:21], v[128:129] op_sel_hi:[1,0,0] neg_lo:[1,0,0] neg_hi:[1,0,0]
	v_mfma_f32_16x16x32_bf16 v[4:7], v[12:15], v[84:87], v[4:7]
	v_mul_f32_e64 v8, v0, v8
	v_mul_f32_e64 v9, v1, v9
	v_exp_f32_e32 v8, v8
	v_exp_f32_e32 v9, v9
	v_mfma_f32_16x16x32_bf16 v[4:7], v[16:19], v[88:91], v[4:7]
	v_add_f32_e64 v8, v8, 1.0
	v_add_f32_e64 v9, v9, 1.0
	v_rcp_f32_e32 v8, v8
	v_rcp_f32_e32 v9, v9
	v_mfma_f32_16x16x32_bf16 v[4:7], v[20:23], v[92:95], v[4:7]
	v_mul_f32_e64 v0, v0, v8
	v_mul_f32_e64 v1, v1, v9
	v_cvt_pk_bf16_f32 v0, v0, v1
	ds_read_u16 v8, v214 offset:128
	ds_read_u16 v9, v214 offset:160
	ds_write_b16 v215, v0
	ds_write_b16_d16_hi v215, v0 offset:32
	ds_read_u16 v0, v214 offset:64
	ds_read_u16 v1, v214 offset:96
	ds_read_u16 v10, v214 offset:192
	ds_read_u16 v11, v214 offset:224
	v_mfma_f32_32x32x16_bf16 v[16:31], v[108:111], v[68:71], 0
	s_waitcnt lgkmcnt(3)
	v_lshlrev_b32_e32 v0, 16, v0
	s_waitcnt lgkmcnt(2)
	v_lshlrev_b32_e32 v1, 16, v1
	v_fma_f32 v0, v176, v0, v2
	v_fma_f32 v1, v177, v1, v3
	v_pk_mul_f32 v[2:3], v[0:1], v[0:1]
	s_nop 4
	v_pk_fma_f32 v[16:17], v[180:181], v[118:119], v[16:17]
	v_pk_fma_f32 v[2:3], v[2:3], s[20:21], v[128:129] op_sel_hi:[1,0,0] neg_lo:[1,0,0] neg_hi:[1,0,0]
	v_pk_fma_f32 v[16:17], v[170:171], v[116:117], v[16:17]
	v_pk_mul_f32 v[2:3], v[0:1], v[2:3]
	s_nop 0
	v_exp_f32_e32 v2, v2
	v_exp_f32_e32 v3, v3
	s_nop 0
	v_pk_add_f32 v[2:3], v[2:3], 1.0 op_sel_hi:[1,0]
	s_nop 0
	v_rcp_f32_e32 v2, v2
	v_rcp_f32_e32 v3, v3
	s_nop 0
	v_pk_mul_f32 v[0:1], v[0:1], v[2:3]
	s_nop 0
	v_cvt_pk_bf16_f32 v0, v0, v1
	ds_write_b16 v215, v0 offset:64
	ds_write_b16_d16_hi v215, v0 offset:96
	v_lshlrev_b32_e32 v1, 16, v9
	v_lshlrev_b32_e32 v0, 16, v8
	v_pk_fma_f32 v[0:1], v[176:177], v[0:1], v[4:5]
	v_add_u32_e32 v4, v141, v148
	v_pk_mul_f32 v[2:3], v[0:1], v[0:1]
	v_ashrrev_i32_e32 v5, 31, v4
	v_pk_fma_f32 v[2:3], v[2:3], s[20:21], v[128:129] op_sel_hi:[1,0,0] neg_lo:[1,0,0] neg_hi:[1,0,0]
	v_lshlrev_b64 v[4:5], 11, v[4:5]
	v_pk_mul_f32 v[2:3], v[0:1], v[2:3]
	v_lshl_add_u64 v[4:5], v[126:127], 0, v[4:5]
	v_exp_f32_e32 v2, v2
	v_exp_f32_e32 v3, v3
	s_nop 0
	v_pk_add_f32 v[2:3], v[2:3], 1.0 op_sel_hi:[1,0]
	s_nop 0
	v_rcp_f32_e32 v2, v2
	v_rcp_f32_e32 v3, v3
	s_nop 0
	v_pk_mul_f32 v[0:1], v[0:1], v[2:3]
	s_nop 0
	v_cvt_pk_bf16_f32 v0, v0, v1
	ds_write_b16 v215, v0 offset:512
	ds_write_b16_d16_hi v215, v0 offset:544
	s_waitcnt lgkmcnt(4)
	v_lshlrev_b32_e32 v1, 16, v11
	v_lshlrev_b32_e32 v0, 16, v10
	v_pk_fma_f32 v[0:1], v[176:177], v[0:1], v[6:7]
	s_nop 0
	v_pk_mul_f32 v[2:3], v[0:1], v[0:1]
	s_nop 0
	v_pk_fma_f32 v[2:3], v[2:3], s[20:21], v[128:129] op_sel_hi:[1,0,0] neg_lo:[1,0,0] neg_hi:[1,0,0]
	s_nop 0
	v_pk_mul_f32 v[2:3], v[0:1], v[2:3]
	s_nop 0
	v_exp_f32_e32 v2, v2
	v_exp_f32_e32 v3, v3
	s_nop 0
	v_pk_add_f32 v[2:3], v[2:3], 1.0 op_sel_hi:[1,0]
	s_nop 0
	v_rcp_f32_e32 v2, v2
	v_rcp_f32_e32 v3, v3
	s_nop 0
	v_pk_mul_f32 v[0:1], v[0:1], v[2:3]
	s_nop 0
	v_cvt_pk_bf16_f32 v0, v0, v1
	ds_write_b16 v215, v0 offset:576
	ds_write_b16_d16_hi v215, v0 offset:608
	s_waitcnt lgkmcnt(0)
	ds_read_b128 v[0:3], v147
	s_waitcnt lgkmcnt(0)
	global_store_dwordx4 v[4:5], v[0:3], off
	s_nop 1
	v_mfma_f32_32x32x16_bf16 v[0:15], v[108:111], v[76:79], 0
	s_waitcnt lgkmcnt(0)
; #define LAS __attribute__((address_space(3)))
; #define LDS_WAIT() asm volatile("s_waitcnt lgkmcnt(0)" ::: "memory")
; __device__ __forceinline__ unsigned cvt2(float lo, float hi) { const f2_t v = {lo, hi}; return __builtin_bit_cast(unsigned, __builtin_convertvector(v, bf2_t)); }
; __device__ __forceinline__ f2v fma2(f2v a, f2v b, f2v c) { return __builtin_elementwise_fma(a, b, c); }
; __device__ __forceinline__ void ssm_phase(Frame& F) {
;     ...
; #pragma unroll
;             for (int s = 0; s < 8; ++s) {
;                 *(LAS bf16x8*)(ut + l31 * 32 + 16 * h) = afr[s];
;                 const f32x16 D0 = __builtin_amdgcn_mfma_f32_32x32x16_bf16(afr[s], bfrag[0], z, 0, 0, 0), D1 = __builtin_amdgcn_mfma_f32_32x32x16_bf16(afr[s], bfrag[1], z, 0, 0, 0),
;                              D2 = __builtin_amdgcn_mfma_f32_32x32x16_bf16(afr[s], bfrag[2], z, 0, 0, 0), D3 = __builtin_amdgcn_mfma_f32_32x32x16_bf16(afr[s], bfrag[3], z, 0, 0, 0);
; #pragma unroll
;                 for (int t = 0; t < 8; ++t) {
;                     const f2v d0 = {D0[2 * t], D0[2 * t + 1]}, d1 = {D1[2 * t], D1[2 * t + 1]}, d2 = {D2[2 * t], D2[2 * t + 1]}, d3 = {D3[2 * t], D3[2 * t + 1]};
;                     const f2v nr0 = fma2(AR0, Sre0, fma2(NAI0, Sim0, d0)), ni0 = fma2(AR0, Sim0, fma2(AI0, Sre0, d2));
;                     const f2v nr1 = fma2(AR1, Sre1, fma2(NAI1, Sim1, d1)), ni1 = fma2(AR1, Sim1, fma2(AI1, Sre1, d3));
;                     Sre0 = nr0; Sim0 = ni0; Sre1 = nr1; Sim1 = ni1;
; #pragma unroll
;                     for (int e = 0; e < 2; ++e) { v2u w; w.x = cvt2(nr0[e], nr1[e]); w.y = cvt2(ni0[e], ni1[e]); *(LAS v2u*)(st + (16 * h + 2 * t + e) * 272 + 8 * l31) = w; }
;                 }
;                 LDS_WAIT(); asm volatile("" ::: "memory");
;                 f32x4 acc0 = (f32x4){0.f, 0.f, 0.f, 0.f}, acc1 = (f32x4){0.f, 0.f, 0.f, 0.f};
; #pragma unroll
;                 for (int ks = 0; ks < 4; ++ks) {
;                     const bf16x8 s0 = *(const LAS bf16x8*)(st + l15 * 272 + 64 * ks + 16 * qq), s1 = *(const LAS bf16x8*)(st + (16 + l15) * 272 + 64 * ks + 16 * qq);
;                     acc0 = __builtin_amdgcn_mfma_f32_16x16x32_bf16(s0, cfrag[ks], acc0, 0, 0, 0); acc1 = __builtin_amdgcn_mfma_f32_16x16x32_bf16(s1, cfrag[ks], acc1, 0, 0, 0); }
	ds_write_b128 v212, v[108:111]
	v_cvt_pk_bf16_f32 v108, v48, v16
	v_cvt_pk_bf16_f32 v110, v49, v17
	s_nop 8
	v_pk_fma_f32 v[0:1], v[174:175], v[116:117], v[0:1]
	s_nop 0
	v_pk_fma_f32 v[0:1], v[170:171], v[118:119], v[0:1]
	v_pk_fma_f32 v[2:3], v[174:175], v[16:17], v[2:3]
	v_pk_fma_f32 v[18:19], v[180:181], v[0:1], v[18:19]
	v_cvt_pk_bf16_f32 v109, v32, v0
	v_cvt_pk_bf16_f32 v111, v33, v1
	v_pk_fma_f32 v[32:33], v[168:169], v[32:33], v[34:35]
	v_pk_fma_f32 v[18:19], v[170:171], v[16:17], v[18:19]
	v_pk_fma_f32 v[0:1], v[170:171], v[0:1], v[2:3]
	v_cvt_pk_bf16_f32 v2, v50, v18
	v_cvt_pk_bf16_f32 v3, v32, v0
	v_cvt_pk_bf16_f32 v16, v51, v19
	v_cvt_pk_bf16_f32 v17, v33, v1
	ds_write2_b64 v149, v[2:3], v[16:17] offset0:68 offset1:102
	v_pk_fma_f32 v[2:3], v[178:179], v[32:33], v[52:53]
	v_pk_fma_f32 v[16:17], v[172:173], v[50:51], v[36:37]
	v_pk_fma_f32 v[20:21], v[180:181], v[0:1], v[20:21]
	v_pk_fma_f32 v[4:5], v[174:175], v[18:19], v[4:5]
	v_pk_fma_f32 v[2:3], v[168:169], v[50:51], v[2:3]
	v_pk_fma_f32 v[16:17], v[168:169], v[32:33], v[16:17]
	v_pk_fma_f32 v[20:21], v[170:171], v[18:19], v[20:21]
	v_pk_fma_f32 v[0:1], v[170:171], v[0:1], v[4:5]
	v_cvt_pk_bf16_f32 v4, v2, v20
	v_cvt_pk_bf16_f32 v5, v16, v0
	v_cvt_pk_bf16_f32 v18, v3, v21
	v_cvt_pk_bf16_f32 v19, v17, v1
	ds_write2_b64 v149, v[4:5], v[18:19] offset0:136 offset1:170
	v_pk_fma_f32 v[4:5], v[178:179], v[16:17], v[54:55]
	v_pk_fma_f32 v[6:7], v[174:175], v[20:21], v[6:7]
	v_pk_fma_f32 v[4:5], v[168:169], v[2:3], v[4:5]
	v_pk_fma_f32 v[2:3], v[172:173], v[2:3], v[38:39]
	ds_write2_b64 v149, v[108:109], v[110:111] offset1:34
	v_pk_fma_f32 v[2:3], v[168:169], v[16:17], v[2:3]
	v_pk_fma_f32 v[16:17], v[180:181], v[0:1], v[22:23]
	v_pk_fma_f32 v[0:1], v[170:171], v[0:1], v[6:7]
	v_pk_fma_f32 v[16:17], v[170:171], v[20:21], v[16:17]
	v_cvt_pk_bf16_f32 v7, v2, v0
	v_cvt_pk_bf16_f32 v6, v4, v16
	v_cvt_pk_bf16_f32 v18, v5, v17
	v_cvt_pk_bf16_f32 v19, v3, v1
	ds_write2_b64 v149, v[6:7], v[18:19] offset0:204 offset1:238
	v_pk_fma_f32 v[6:7], v[178:179], v[2:3], v[56:57]
	v_pk_fma_f32 v[8:9], v[174:175], v[16:17], v[8:9]
	v_pk_fma_f32 v[6:7], v[168:169], v[4:5], v[6:7]
	v_pk_fma_f32 v[4:5], v[172:173], v[4:5], v[40:41]
	s_nop 0
	v_pk_fma_f32 v[2:3], v[168:169], v[2:3], v[4:5]
	v_pk_fma_f32 v[4:5], v[180:181], v[0:1], v[24:25]
	v_pk_fma_f32 v[0:1], v[170:171], v[0:1], v[8:9]
	v_pk_fma_f32 v[4:5], v[170:171], v[16:17], v[4:5]
	v_cvt_pk_bf16_f32 v9, v2, v0
	v_cvt_pk_bf16_f32 v8, v6, v4
	v_cvt_pk_bf16_f32 v16, v7, v5
	v_cvt_pk_bf16_f32 v17, v3, v1
	ds_write2_b64 v146, v[8:9], v[16:17] offset0:16 offset1:50
	v_pk_fma_f32 v[8:9], v[178:179], v[2:3], v[58:59]
	s_nop 0
	v_pk_fma_f32 v[8:9], v[168:169], v[6:7], v[8:9]
	v_pk_fma_f32 v[6:7], v[172:173], v[6:7], v[42:43]
	s_nop 0
	v_pk_fma_f32 v[2:3], v[168:169], v[2:3], v[6:7]
	v_pk_fma_f32 v[6:7], v[180:181], v[0:1], v[26:27]
	s_nop 0
	v_pk_fma_f32 v[6:7], v[170:171], v[4:5], v[6:7]
	v_pk_fma_f32 v[4:5], v[174:175], v[4:5], v[10:11]
	v_cvt_pk_bf16_f32 v10, v9, v7
	v_pk_fma_f32 v[0:1], v[170:171], v[0:1], v[4:5]
	v_cvt_pk_bf16_f32 v4, v8, v6
	v_cvt_pk_bf16_f32 v5, v2, v0
	v_cvt_pk_bf16_f32 v11, v3, v1
	ds_write2_b64 v146, v[4:5], v[10:11] offset0:84 offset1:118
	v_pk_fma_f32 v[4:5], v[178:179], v[2:3], v[60:61]
	s_nop 0
	v_pk_fma_f32 v[4:5], v[168:169], v[8:9], v[4:5]
	v_pk_fma_f32 v[8:9], v[172:173], v[8:9], v[44:45]
	s_nop 0
	v_pk_fma_f32 v[2:3], v[168:169], v[2:3], v[8:9]
	v_pk_fma_f32 v[8:9], v[180:181], v[0:1], v[28:29]
	s_nop 0
	v_pk_fma_f32 v[8:9], v[170:171], v[6:7], v[8:9]
	v_pk_fma_f32 v[6:7], v[174:175], v[6:7], v[12:13]
	v_cvt_pk_bf16_f32 v10, v5, v9
	v_pk_fma_f32 v[0:1], v[170:171], v[0:1], v[6:7]
	v_cvt_pk_bf16_f32 v6, v4, v8
	v_cvt_pk_bf16_f32 v7, v2, v0
	v_cvt_pk_bf16_f32 v11, v3, v1
	ds_write2_b64 v146, v[6:7], v[10:11] offset0:152 offset1:186
	v_pk_fma_f32 v[6:7], v[178:179], v[2:3], v[62:63]
	s_waitcnt vmcnt(6)
	v_mfma_f32_32x32x16_bf16 v[48:63], v[104:107], v[64:67], 0
	v_fma_f32 v108, v168, v4, v6
	v_fma_f32 v109, v169, v5, v7
	v_fma_f32 v4, v172, v4, v46
	v_fma_f32 v5, v173, v5, v47
	v_fma_f32 v110, v168, v2, v4
	v_fma_f32 v111, v169, v3, v5
	v_pk_fma_f32 v[2:3], v[180:181], v[0:1], v[30:31]
	s_nop 4
	v_pk_fma_f32 v[48:49], v[178:179], v[110:111], v[48:49]
	v_pk_fma_f32 v[112:113], v[170:171], v[8:9], v[2:3]
	v_pk_fma_f32 v[2:3], v[174:175], v[8:9], v[14:15]
	v_mfma_f32_32x32x16_bf16 v[32:47], v[104:107], v[72:75], 0
	v_fma_f32 v114, v170, v0, v2
	v_fma_f32 v115, v171, v1, v3
	v_cvt_pk_bf16_f32 v0, v108, v112
	v_cvt_pk_bf16_f32 v1, v110, v114
	v_cvt_pk_bf16_f32 v2, v109, v113
	v_cvt_pk_bf16_f32 v3, v111, v115
	ds_write2_b64 v146, v[0:1], v[2:3] offset0:220 offset1:254
	s_waitcnt lgkmcnt(0)
	ds_read_b128 v[0:3], v213 offset:32768
	ds_read_b128 v[4:7], v213 offset:37120
	s_waitcnt lgkmcnt(1)
	v_mfma_f32_16x16x32_bf16 v[0:3], v[0:3], v[80:83], 0
	ds_read_b128 v[8:11], v213 offset:32832
	ds_read_b128 v[12:15], v213 offset:37184
	v_pk_fma_f32 v[32:33], v[172:173], v[108:109], v[32:33]
	v_pk_fma_f32 v[48:49], v[168:169], v[108:109], v[48:49]
	s_waitcnt lgkmcnt(1)
	v_mfma_f32_16x16x32_bf16 v[0:3], v[8:11], v[84:87], v[0:3]
	ds_read_b128 v[8:11], v213 offset:32896
	ds_read_b128 v[16:19], v213 offset:37248
	v_pk_fma_f32 v[32:33], v[168:169], v[110:111], v[32:33]
	v_pk_fma_f32 v[34:35], v[172:173], v[48:49], v[34:35]
	s_waitcnt lgkmcnt(1)
	v_mfma_f32_16x16x32_bf16 v[0:3], v[8:11], v[88:91], v[0:3]
	ds_read_b128 v[8:11], v213 offset:32960
	ds_read_b128 v[20:23], v213 offset:37312
	v_pk_fma_f32 v[50:51], v[178:179], v[32:33], v[50:51]
	s_waitcnt lgkmcnt(1)
; #define LAS __attribute__((address_space(3)))
; #define LDS_WAIT() asm volatile("s_waitcnt lgkmcnt(0)" ::: "memory")
; __device__ __forceinline__ void ssm_phase(Frame& F) {
;     ...
; #pragma unroll
;             for (int s = 0; s < 8; ++s) {
;                 *(LAS bf16x8*)(ut + l31 * 32 + 16 * h) = afr[s];
;                 const f32x16 D0 = __builtin_amdgcn_mfma_f32_32x32x16_bf16(afr[s], bfrag[0], z, 0, 0, 0), D1 = __builtin_amdgcn_mfma_f32_32x32x16_bf16(afr[s], bfrag[1], z, 0, 0, 0),
;                              D2 = __builtin_amdgcn_mfma_f32_32x32x16_bf16(afr[s], bfrag[2], z, 0, 0, 0), D3 = __builtin_amdgcn_mfma_f32_32x32x16_bf16(afr[s], bfrag[3], z, 0, 0, 0);
; #pragma unroll
;                 for (int t = 0; t < 8; ++t) {
;                     const f2v d0 = {D0[2 * t], D0[2 * t + 1]}, d1 = {D1[2 * t], D1[2 * t + 1]}, d2 = {D2[2 * t], D2[2 * t + 1]}, d3 = {D3[2 * t], D3[2 * t + 1]};
;                     const f2v nr0 = fma2(AR0, Sre0, fma2(NAI0, Sim0, d0)), ni0 = fma2(AR0, Sim0, fma2(AI0, Sre0, d2));
;                     const f2v nr1 = fma2(AR1, Sre1, fma2(NAI1, Sim1, d1)), ni1 = fma2(AR1, Sim1, fma2(AI1, Sre1, d3));
;                     Sre0 = nr0; Sim0 = ni0; Sre1 = nr1; Sim1 = ni1;
; #pragma unroll
;                     for (int e = 0; e < 2; ++e) { v2u w; w.x = cvt2(nr0[e], nr1[e]); w.y = cvt2(ni0[e], ni1[e]); *(LAS v2u*)(st + (16 * h + 2 * t + e) * 272 + 8 * l31) = w; }
;                 }
;                 LDS_WAIT(); asm volatile("" ::: "memory");
;                 f32x4 acc0 = (f32x4){0.f, 0.f, 0.f, 0.f}, acc1 = (f32x4){0.f, 0.f, 0.f, 0.f};
; #pragma unroll
;                 for (int ks = 0; ks < 4; ++ks) {
;                     const bf16x8 s0 = *(const LAS bf16x8*)(st + l15 * 272 + 64 * ks + 16 * qq), s1 = *(const LAS bf16x8*)(st + (16 + l15) * 272 + 64 * ks + 16 * qq);
;                     acc0 = __builtin_amdgcn_mfma_f32_16x16x32_bf16(s0, cfrag[ks], acc0, 0, 0, 0); acc1 = __builtin_amdgcn_mfma_f32_16x16x32_bf16(s1, cfrag[ks], acc1, 0, 0, 0); }
;                 float uu[2][4];
; #pragma unroll
;                 for (int rb = 0; rb < 2; ++rb)
; #pragma unroll
;                     for (int i2 = 0; i2 < 4; ++i2) uu[rb][i2] = bf1(*(const LAS bf16*)(ut + (i2 + 4 * rb + 8 * qq) * 32 + 2 * l15));
; #pragma unroll
;                 for (int rb = 0; rb < 2; ++rb)
; #pragma unroll
;                     for (int i2 = 0; i2 < 4; i2 += 2) {
	v_mfma_f32_16x16x32_bf16 v[0:3], v[8:11], v[92:95], v[0:3]
	ds_read_u16 v8, v214
	ds_read_u16 v9, v214 offset:32
	v_pk_fma_f32 v[50:51], v[168:169], v[48:49], v[50:51]
	s_waitcnt lgkmcnt(1)
	v_lshlrev_b32_e32 v8, 16, v8
	s_waitcnt lgkmcnt(0)
	v_lshlrev_b32_e32 v9, 16, v9
	s_nop 0
	v_pk_fma_f32 v[0:1], v[176:177], v[8:9], v[0:1]
	v_mfma_f32_16x16x32_bf16 v[4:7], v[4:7], v[80:83], 0
	v_mul_f32_e64 v8, v0, v0
	v_mul_f32_e64 v9, v1, v1
	v_pk_fma_f32 v[8:9], v[8:9], s[20:21], v[128:129] op_sel_hi:[1,0,0] neg_lo:[1,0,0] neg_hi:[1,0,0]
	v_mfma_f32_16x16x32_bf16 v[4:7], v[12:15], v[84:87], v[4:7]
	v_mul_f32_e64 v8, v0, v8
	v_mul_f32_e64 v9, v1, v9
	v_exp_f32_e32 v8, v8
	v_exp_f32_e32 v9, v9
	v_mfma_f32_16x16x32_bf16 v[4:7], v[16:19], v[88:91], v[4:7]
	v_add_f32_e64 v8, v8, 1.0
	v_add_f32_e64 v9, v9, 1.0
	v_rcp_f32_e32 v8, v8
	v_rcp_f32_e32 v9, v9
	v_mfma_f32_16x16x32_bf16 v[4:7], v[20:23], v[92:95], v[4:7]
	v_mul_f32_e64 v0, v0, v8
	v_mul_f32_e64 v1, v1, v9
	v_cvt_pk_bf16_f32 v0, v0, v1
	ds_read_u16 v8, v214 offset:128
	ds_read_u16 v9, v214 offset:160
	ds_write_b16 v215, v0
	ds_write_b16_d16_hi v215, v0 offset:32
	ds_read_u16 v0, v214 offset:64
	ds_read_u16 v1, v214 offset:96
	ds_read_u16 v10, v214 offset:192
	ds_read_u16 v11, v214 offset:224
	v_mfma_f32_32x32x16_bf16 v[16:31], v[104:107], v[76:79], 0
	s_waitcnt lgkmcnt(3)
	v_lshlrev_b32_e32 v0, 16, v0
	s_waitcnt lgkmcnt(2)
	v_lshlrev_b32_e32 v1, 16, v1
	v_fma_f32 v0, v176, v0, v2
	v_fma_f32 v1, v177, v1, v3
	v_pk_mul_f32 v[2:3], v[0:1], v[0:1]
	s_nop 4
	v_pk_fma_f32 v[16:17], v[174:175], v[112:113], v[16:17]
	v_pk_fma_f32 v[2:3], v[2:3], s[20:21], v[128:129] op_sel_hi:[1,0,0] neg_lo:[1,0,0] neg_hi:[1,0,0]
	v_pk_fma_f32 v[16:17], v[170:171], v[114:115], v[16:17]
	v_pk_mul_f32 v[2:3], v[0:1], v[2:3]
	s_nop 0
	v_exp_f32_e32 v2, v2
	v_exp_f32_e32 v3, v3
	s_nop 0
	v_pk_add_f32 v[2:3], v[2:3], 1.0 op_sel_hi:[1,0]
	s_nop 0
	v_rcp_f32_e32 v2, v2
	v_rcp_f32_e32 v3, v3
	s_nop 0
	v_pk_mul_f32 v[0:1], v[0:1], v[2:3]
	s_nop 0
	v_cvt_pk_bf16_f32 v0, v0, v1
	ds_write_b16 v215, v0 offset:64
	ds_write_b16_d16_hi v215, v0 offset:96
	v_lshlrev_b32_e32 v1, 16, v9
	v_lshlrev_b32_e32 v0, 16, v8
	v_pk_fma_f32 v[0:1], v[176:177], v[0:1], v[4:5]
	v_add_u32_e32 v4, v142, v148
	v_pk_mul_f32 v[2:3], v[0:1], v[0:1]
	v_ashrrev_i32_e32 v5, 31, v4
	v_pk_fma_f32 v[2:3], v[2:3], s[20:21], v[128:129] op_sel_hi:[1,0,0] neg_lo:[1,0,0] neg_hi:[1,0,0]
	v_lshlrev_b64 v[4:5], 11, v[4:5]
	v_pk_mul_f32 v[2:3], v[0:1], v[2:3]
	v_lshl_add_u64 v[4:5], v[126:127], 0, v[4:5]
	v_exp_f32_e32 v2, v2
	v_exp_f32_e32 v3, v3
	s_nop 0
	v_pk_add_f32 v[2:3], v[2:3], 1.0 op_sel_hi:[1,0]
	s_nop 0
	v_rcp_f32_e32 v2, v2
	v_rcp_f32_e32 v3, v3
	s_nop 0
	v_pk_mul_f32 v[0:1], v[0:1], v[2:3]
	s_nop 0
	v_cvt_pk_bf16_f32 v0, v0, v1
	ds_write_b16 v215, v0 offset:512
	ds_write_b16_d16_hi v215, v0 offset:544
	s_waitcnt lgkmcnt(4)
	v_lshlrev_b32_e32 v1, 16, v11
	v_lshlrev_b32_e32 v0, 16, v10
	v_pk_fma_f32 v[0:1], v[176:177], v[0:1], v[6:7]
	s_nop 0
	v_pk_mul_f32 v[2:3], v[0:1], v[0:1]
	s_nop 0
	v_pk_fma_f32 v[2:3], v[2:3], s[20:21], v[128:129] op_sel_hi:[1,0,0] neg_lo:[1,0,0] neg_hi:[1,0,0]
	s_nop 0
	v_pk_mul_f32 v[2:3], v[0:1], v[2:3]
	s_nop 0
	v_exp_f32_e32 v2, v2
	v_exp_f32_e32 v3, v3
	s_nop 0
	v_pk_add_f32 v[2:3], v[2:3], 1.0 op_sel_hi:[1,0]
	s_nop 0
	v_rcp_f32_e32 v2, v2
	v_rcp_f32_e32 v3, v3
	s_nop 0
	v_pk_mul_f32 v[0:1], v[0:1], v[2:3]
	s_nop 0
	v_cvt_pk_bf16_f32 v0, v0, v1
	ds_write_b16 v215, v0 offset:576
	ds_write_b16_d16_hi v215, v0 offset:608
	s_waitcnt lgkmcnt(0)
	ds_read_b128 v[0:3], v147
	s_waitcnt lgkmcnt(0)
	global_store_dwordx4 v[4:5], v[0:3], off
	s_nop 1
	v_mfma_f32_32x32x16_bf16 v[0:15], v[104:107], v[68:71], 0
	s_waitcnt lgkmcnt(0)
	ds_write_b128 v212, v[104:107]
	v_cvt_pk_bf16_f32 v105, v32, v16
	v_cvt_pk_bf16_f32 v107, v33, v17
	v_fma_f32 v32, v168, v32, v34
	v_fma_f32 v33, v169, v33, v35
	s_nop 6
	v_pk_fma_f32 v[0:1], v[180:181], v[114:115], v[0:1]
	s_nop 0
	v_pk_fma_f32 v[0:1], v[170:171], v[112:113], v[0:1]
	v_pk_fma_f32 v[2:3], v[180:181], v[16:17], v[2:3]
	v_cvt_pk_bf16_f32 v104, v48, v0
	v_cvt_pk_bf16_f32 v106, v49, v1
	v_pk_fma_f32 v[2:3], v[170:171], v[0:1], v[2:3]
	v_pk_fma_f32 v[0:1], v[174:175], v[0:1], v[18:19]
	v_cvt_pk_bf16_f32 v18, v51, v3
	v_pk_fma_f32 v[0:1], v[170:171], v[16:17], v[0:1]
	v_cvt_pk_bf16_f32 v16, v50, v2
	v_cvt_pk_bf16_f32 v17, v32, v0
	v_cvt_pk_bf16_f32 v19, v33, v1
	v_pk_fma_f32 v[4:5], v[180:181], v[0:1], v[4:5]
	ds_write2_b64 v149, v[16:17], v[18:19] offset0:68 offset1:102
	v_pk_fma_f32 v[16:17], v[178:179], v[32:33], v[52:53]
	v_pk_fma_f32 v[18:19], v[172:173], v[50:51], v[36:37]
	v_pk_fma_f32 v[4:5], v[170:171], v[2:3], v[4:5]
	v_pk_fma_f32 v[2:3], v[174:175], v[2:3], v[20:21]
	v_pk_fma_f32 v[16:17], v[168:169], v[50:51], v[16:17]
	v_pk_fma_f32 v[18:19], v[168:169], v[32:33], v[18:19]
	v_pk_fma_f32 v[0:1], v[170:171], v[0:1], v[2:3]
	v_cvt_pk_bf16_f32 v2, v16, v4
	v_cvt_pk_bf16_f32 v3, v18, v0
	v_cvt_pk_bf16_f32 v20, v17, v5
	v_cvt_pk_bf16_f32 v21, v19, v1
	ds_write2_b64 v149, v[2:3], v[20:21] offset0:136 offset1:170
	v_pk_fma_f32 v[2:3], v[178:179], v[18:19], v[54:55]
	v_pk_fma_f32 v[6:7], v[180:181], v[0:1], v[6:7]
	v_pk_fma_f32 v[2:3], v[168:169], v[16:17], v[2:3]
	v_pk_fma_f32 v[16:17], v[172:173], v[16:17], v[38:39]
	v_pk_fma_f32 v[6:7], v[170:171], v[4:5], v[6:7]
	v_pk_fma_f32 v[4:5], v[174:175], v[4:5], v[22:23]
	v_pk_fma_f32 v[16:17], v[168:169], v[18:19], v[16:17]
	v_pk_fma_f32 v[0:1], v[170:171], v[0:1], v[4:5]
	v_cvt_pk_bf16_f32 v4, v2, v6
	v_cvt_pk_bf16_f32 v5, v16, v0
	v_cvt_pk_bf16_f32 v18, v3, v7
	v_cvt_pk_bf16_f32 v19, v17, v1
	ds_write2_b64 v149, v[4:5], v[18:19] offset0:204 offset1:238
; #define LAS __attribute__((address_space(3)))
; #define LDS_WAIT() asm volatile("s_waitcnt lgkmcnt(0)" ::: "memory")
; __device__ __forceinline__ float bf1(bf16 v) { return __uint_as_float((unsigned)v << 16); }
; __device__ __forceinline__ void ssm_phase(Frame& F) {
;     ...
; #pragma unroll
;             for (int s = 0; s < 8; ++s) {
;                 *(LAS bf16x8*)(ut + l31 * 32 + 16 * h) = afr[s];
;                 const f32x16 D0 = __builtin_amdgcn_mfma_f32_32x32x16_bf16(afr[s], bfrag[0], z, 0, 0, 0), D1 = __builtin_amdgcn_mfma_f32_32x32x16_bf16(afr[s], bfrag[1], z, 0, 0, 0),
;                              D2 = __builtin_amdgcn_mfma_f32_32x32x16_bf16(afr[s], bfrag[2], z, 0, 0, 0), D3 = __builtin_amdgcn_mfma_f32_32x32x16_bf16(afr[s], bfrag[3], z, 0, 0, 0);
; #pragma unroll
;                 for (int t = 0; t < 8; ++t) {
;                     const f2v d0 = {D0[2 * t], D0[2 * t + 1]}, d1 = {D1[2 * t], D1[2 * t + 1]}, d2 = {D2[2 * t], D2[2 * t + 1]}, d3 = {D3[2 * t], D3[2 * t + 1]};
;                     const f2v nr0 = fma2(AR0, Sre0, fma2(NAI0, Sim0, d0)), ni0 = fma2(AR0, Sim0, fma2(AI0, Sre0, d2));
;                     const f2v nr1 = fma2(AR1, Sre1, fma2(NAI1, Sim1, d1)), ni1 = fma2(AR1, Sim1, fma2(AI1, Sre1, d3));
;                     Sre0 = nr0; Sim0 = ni0; Sre1 = nr1; Sim1 = ni1;
; #pragma unroll
;                     for (int e = 0; e < 2; ++e) { v2u w; w.x = cvt2(nr0[e], nr1[e]); w.y = cvt2(ni0[e], ni1[e]); *(LAS v2u*)(st + (16 * h + 2 * t + e) * 272 + 8 * l31) = w; }
;                 }
;                 LDS_WAIT(); asm volatile("" ::: "memory");
;                 f32x4 acc0 = (f32x4){0.f, 0.f, 0.f, 0.f}, acc1 = (f32x4){0.f, 0.f, 0.f, 0.f};
; #pragma unroll
;                 for (int ks = 0; ks < 4; ++ks) {
;                     const bf16x8 s0 = *(const LAS bf16x8*)(st + l15 * 272 + 64 * ks + 16 * qq), s1 = *(const LAS bf16x8*)(st + (16 + l15) * 272 + 64 * ks + 16 * qq);
;                     acc0 = __builtin_amdgcn_mfma_f32_16x16x32_bf16(s0, cfrag[ks], acc0, 0, 0, 0); acc1 = __builtin_amdgcn_mfma_f32_16x16x32_bf16(s1, cfrag[ks], acc1, 0, 0, 0); }
;                 float uu[2][4];
; #pragma unroll
;                 for (int rb = 0; rb < 2; ++rb)
; #pragma unroll
;                     for (int i2 = 0; i2 < 4; ++i2) uu[rb][i2] = bf1(*(const LAS bf16*)(ut + (i2 + 4 * rb + 8 * qq) * 32 + 2 * l15));
	v_pk_fma_f32 v[4:5], v[178:179], v[16:17], v[56:57]
	v_pk_fma_f32 v[8:9], v[180:181], v[0:1], v[8:9]
	v_pk_fma_f32 v[4:5], v[168:169], v[2:3], v[4:5]
	v_pk_fma_f32 v[2:3], v[172:173], v[2:3], v[40:41]
	v_pk_fma_f32 v[8:9], v[170:171], v[6:7], v[8:9]
	v_pk_fma_f32 v[6:7], v[174:175], v[6:7], v[24:25]
	v_pk_fma_f32 v[2:3], v[168:169], v[16:17], v[2:3]
	v_pk_fma_f32 v[0:1], v[170:171], v[0:1], v[6:7]
	v_cvt_pk_bf16_f32 v6, v4, v8
	v_cvt_pk_bf16_f32 v7, v2, v0
	v_cvt_pk_bf16_f32 v16, v5, v9
	v_cvt_pk_bf16_f32 v17, v3, v1
	ds_write2_b64 v146, v[6:7], v[16:17] offset0:16 offset1:50
	v_pk_fma_f32 v[6:7], v[178:179], v[2:3], v[58:59]
	ds_write2_b64 v149, v[104:105], v[106:107] offset1:34
	v_pk_fma_f32 v[6:7], v[168:169], v[4:5], v[6:7]
	v_pk_fma_f32 v[4:5], v[172:173], v[4:5], v[42:43]
	s_nop 0
	v_pk_fma_f32 v[2:3], v[168:169], v[2:3], v[4:5]
	v_pk_fma_f32 v[4:5], v[180:181], v[0:1], v[10:11]
	s_nop 0
	v_pk_fma_f32 v[4:5], v[170:171], v[8:9], v[4:5]
	v_pk_fma_f32 v[8:9], v[174:175], v[8:9], v[26:27]
	v_cvt_pk_bf16_f32 v10, v7, v5
	v_pk_fma_f32 v[0:1], v[170:171], v[0:1], v[8:9]
	v_cvt_pk_bf16_f32 v8, v6, v4
	v_cvt_pk_bf16_f32 v9, v2, v0
	v_cvt_pk_bf16_f32 v11, v3, v1
	ds_write2_b64 v146, v[8:9], v[10:11] offset0:84 offset1:118
	v_pk_fma_f32 v[8:9], v[178:179], v[2:3], v[60:61]
	s_nop 0
	v_pk_fma_f32 v[8:9], v[168:169], v[6:7], v[8:9]
	v_pk_fma_f32 v[6:7], v[172:173], v[6:7], v[44:45]
	s_nop 0
	v_pk_fma_f32 v[2:3], v[168:169], v[2:3], v[6:7]
	v_pk_fma_f32 v[6:7], v[180:181], v[0:1], v[12:13]
	s_nop 0
	v_pk_fma_f32 v[6:7], v[170:171], v[4:5], v[6:7]
	v_pk_fma_f32 v[4:5], v[174:175], v[4:5], v[28:29]
	v_cvt_pk_bf16_f32 v10, v9, v7
	v_pk_fma_f32 v[0:1], v[170:171], v[0:1], v[4:5]
	v_cvt_pk_bf16_f32 v4, v8, v6
	v_cvt_pk_bf16_f32 v5, v2, v0
	v_cvt_pk_bf16_f32 v11, v3, v1
	ds_write2_b64 v146, v[4:5], v[10:11] offset0:152 offset1:186
	v_pk_fma_f32 v[4:5], v[178:179], v[2:3], v[62:63]
	s_waitcnt vmcnt(6)
	v_mfma_f32_32x32x16_bf16 v[48:63], v[100:103], v[64:67], 0
	v_fma_f32 v104, v168, v8, v4
	v_fma_f32 v105, v169, v9, v5
	v_fma_f32 v4, v172, v8, v46
	v_fma_f32 v5, v173, v9, v47
	v_fma_f32 v108, v168, v2, v4
	v_fma_f32 v109, v169, v3, v5
	v_pk_fma_f32 v[2:3], v[180:181], v[0:1], v[14:15]
	s_nop 4
	v_pk_fma_f32 v[48:49], v[178:179], v[108:109], v[48:49]
	v_pk_fma_f32 v[106:107], v[170:171], v[6:7], v[2:3]
	v_pk_fma_f32 v[2:3], v[174:175], v[6:7], v[30:31]
	v_mfma_f32_32x32x16_bf16 v[32:47], v[100:103], v[72:75], 0
	v_fma_f32 v110, v170, v0, v2
	v_fma_f32 v111, v171, v1, v3
	v_cvt_pk_bf16_f32 v0, v104, v106
	v_cvt_pk_bf16_f32 v1, v108, v110
	v_cvt_pk_bf16_f32 v2, v105, v107
	v_cvt_pk_bf16_f32 v3, v109, v111
	ds_write2_b64 v146, v[0:1], v[2:3] offset0:220 offset1:254
	s_waitcnt lgkmcnt(0)
	ds_read_b128 v[0:3], v213 offset:32768
	ds_read_b128 v[4:7], v213 offset:37120
	s_waitcnt lgkmcnt(1)
	v_mfma_f32_16x16x32_bf16 v[0:3], v[0:3], v[80:83], 0
	ds_read_b128 v[8:11], v213 offset:32832
	ds_read_b128 v[12:15], v213 offset:37184
	v_pk_fma_f32 v[32:33], v[172:173], v[104:105], v[32:33]
	v_pk_fma_f32 v[48:49], v[168:169], v[104:105], v[48:49]
	s_waitcnt lgkmcnt(1)
	v_mfma_f32_16x16x32_bf16 v[0:3], v[8:11], v[84:87], v[0:3]
	ds_read_b128 v[8:11], v213 offset:32896
	ds_read_b128 v[16:19], v213 offset:37248
	v_pk_fma_f32 v[32:33], v[168:169], v[108:109], v[32:33]
	v_pk_fma_f32 v[34:35], v[172:173], v[48:49], v[34:35]
	s_waitcnt lgkmcnt(1)
	v_mfma_f32_16x16x32_bf16 v[0:3], v[8:11], v[88:91], v[0:3]
	ds_read_b128 v[8:11], v213 offset:32960
	ds_read_b128 v[20:23], v213 offset:37312
	v_pk_fma_f32 v[50:51], v[178:179], v[32:33], v[50:51]
	s_waitcnt lgkmcnt(1)
	v_mfma_f32_16x16x32_bf16 v[0:3], v[8:11], v[92:95], v[0:3]
	ds_read_u16 v8, v214
	ds_read_u16 v9, v214 offset:32
	v_pk_fma_f32 v[50:51], v[168:169], v[48:49], v[50:51]
	s_waitcnt lgkmcnt(1)
	v_lshlrev_b32_e32 v8, 16, v8
	s_waitcnt lgkmcnt(0)
	v_lshlrev_b32_e32 v9, 16, v9
	s_nop 0
	v_pk_fma_f32 v[0:1], v[176:177], v[8:9], v[0:1]
	v_mfma_f32_16x16x32_bf16 v[4:7], v[4:7], v[80:83], 0
	v_mul_f32_e64 v8, v0, v0
	v_mul_f32_e64 v9, v1, v1
	v_pk_fma_f32 v[8:9], v[8:9], s[20:21], v[128:129] op_sel_hi:[1,0,0] neg_lo:[1,0,0] neg_hi:[1,0,0]
	v_mfma_f32_16x16x32_bf16 v[4:7], v[12:15], v[84:87], v[4:7]
	v_mul_f32_e64 v8, v0, v8
	v_mul_f32_e64 v9, v1, v9
	v_exp_f32_e32 v8, v8
	v_exp_f32_e32 v9, v9
	v_mfma_f32_16x16x32_bf16 v[4:7], v[16:19], v[88:91], v[4:7]
	v_add_f32_e64 v8, v8, 1.0
	v_add_f32_e64 v9, v9, 1.0
	v_rcp_f32_e32 v8, v8
	v_rcp_f32_e32 v9, v9
	v_mfma_f32_16x16x32_bf16 v[4:7], v[20:23], v[92:95], v[4:7]
	v_mul_f32_e64 v0, v0, v8
	v_mul_f32_e64 v1, v1, v9
	v_cvt_pk_bf16_f32 v0, v0, v1
	ds_read_u16 v8, v214 offset:128
	ds_read_u16 v9, v214 offset:160
	ds_write_b16 v215, v0
	ds_write_b16_d16_hi v215, v0 offset:32
	ds_read_u16 v0, v214 offset:64
	ds_read_u16 v1, v214 offset:96
	ds_read_u16 v10, v214 offset:192
	ds_read_u16 v11, v214 offset:224
	v_mfma_f32_32x32x16_bf16 v[16:31], v[100:103], v[68:71], 0
	s_waitcnt lgkmcnt(3)
	v_lshlrev_b32_e32 v0, 16, v0
	s_waitcnt lgkmcnt(2)
; __device__ __forceinline__ void ssm_phase(Frame& F) {
;     ...
; #pragma unroll
;             for (int s = 0; s < 8; ++s) {
;                 *(LAS bf16x8*)(ut + l31 * 32 + 16 * h) = afr[s];
;                 const f32x16 D0 = __builtin_amdgcn_mfma_f32_32x32x16_bf16(afr[s], bfrag[0], z, 0, 0, 0), D1 = __builtin_amdgcn_mfma_f32_32x32x16_bf16(afr[s], bfrag[1], z, 0, 0, 0),
;                              D2 = __builtin_amdgcn_mfma_f32_32x32x16_bf16(afr[s], bfrag[2], z, 0, 0, 0), D3 = __builtin_amdgcn_mfma_f32_32x32x16_bf16(afr[s], bfrag[3], z, 0, 0, 0);
; #pragma unroll
;                 for (int t = 0; t < 8; ++t) {
;     ...
;                 f32x4 acc0 = (f32x4){0.f, 0.f, 0.f, 0.f}, acc1 = (f32x4){0.f, 0.f, 0.f, 0.f};
; #pragma unroll
;                 for (int ks = 0; ks < 4; ++ks) {
;                     const bf16x8 s0 = *(const LAS bf16x8*)(st + l15 * 272 + 64 * ks + 16 * qq), s1 = *(const LAS bf16x8*)(st + (16 + l15) * 272 + 64 * ks + 16 * qq);
;                     acc0 = __builtin_amdgcn_mfma_f32_16x16x32_bf16(s0, cfrag[ks], acc0, 0, 0, 0); acc1 = __builtin_amdgcn_mfma_f32_16x16x32_bf16(s1, cfrag[ks], acc1, 0, 0, 0); }
;                 float uu[2][4];
; #pragma unroll
;                 for (int rb = 0; rb < 2; ++rb)
; #pragma unroll
;                     for (int i2 = 0; i2 < 4; ++i2) uu[rb][i2] = bf1(*(const LAS bf16*)(ut + (i2 + 4 * rb + 8 * qq) * 32 + 2 * l15));
; #pragma unroll
;                 for (int rb = 0; rb < 2; ++rb)
; #pragma unroll
;                     for (int i2 = 0; i2 < 4; i2 += 2) {
;                         f2v y; y.x = (rb == 0 ? acc0[i2] : acc1[i2]) + dsk * uu[rb][i2]; y.y = (rb == 0 ? acc0[i2 + 1] : acc1[i2 + 1]) + dsk * uu[rb][i2 + 1];
;                         const f2v gq = gelu_tanh2(y); const unsigned w = cvt2(gq.x, gq.y);
;                         *(LAS bf16*)(yt + (16 * rb + 4 * qq + i2) * 32 + 2 * l15) = (bf16)(w & 0xffffu); *(LAS bf16*)(yt + (16 * rb + 4 * qq + i2 + 1) * 32 + 2 * l15) = (bf16)(w >> 16); }
;                 LDS_WAIT(); asm volatile("" ::: "memory");
;                 { const int R = lane >> 1, hf = lane & 1; const v4u yv = *(const LAS v4u*)(yt + lane * 16);
;                   const int chunk = F.wave + 8 * (2 * (R >> 4) + (R & 1)) + 32 * it, tok = 8 * s + ((R & 15) >> 1);
;                   *(GAS v4u*)(gb + ((size_t)(b * SEQ + chunk * 64 + tok)) * SW + g * SG + 8 * hf) = yv; }
	v_lshlrev_b32_e32 v1, 16, v1
	v_fma_f32 v0, v176, v0, v2
	v_fma_f32 v1, v177, v1, v3
	v_pk_mul_f32 v[2:3], v[0:1], v[0:1]
	s_nop 4
	v_pk_fma_f32 v[16:17], v[180:181], v[110:111], v[16:17]
	v_pk_fma_f32 v[2:3], v[2:3], s[20:21], v[128:129] op_sel_hi:[1,0,0] neg_lo:[1,0,0] neg_hi:[1,0,0]
	v_pk_fma_f32 v[16:17], v[170:171], v[106:107], v[16:17]
	v_pk_mul_f32 v[2:3], v[0:1], v[2:3]
	s_nop 0
	v_exp_f32_e32 v2, v2
	v_exp_f32_e32 v3, v3
	s_nop 0
	v_pk_add_f32 v[2:3], v[2:3], 1.0 op_sel_hi:[1,0]
	s_nop 0
	v_rcp_f32_e32 v2, v2
	v_rcp_f32_e32 v3, v3
	s_nop 0
	v_pk_mul_f32 v[0:1], v[0:1], v[2:3]
	s_nop 0
	v_cvt_pk_bf16_f32 v0, v0, v1
	ds_write_b16 v215, v0 offset:64
	ds_write_b16_d16_hi v215, v0 offset:96
	v_lshlrev_b32_e32 v1, 16, v9
	v_lshlrev_b32_e32 v0, 16, v8
	v_pk_fma_f32 v[0:1], v[176:177], v[0:1], v[4:5]
	v_add_u32_e32 v4, v143, v148
	v_pk_mul_f32 v[2:3], v[0:1], v[0:1]
	v_ashrrev_i32_e32 v5, 31, v4
	v_pk_fma_f32 v[2:3], v[2:3], s[20:21], v[128:129] op_sel_hi:[1,0,0] neg_lo:[1,0,0] neg_hi:[1,0,0]
	v_lshlrev_b64 v[4:5], 11, v[4:5]
	v_pk_mul_f32 v[2:3], v[0:1], v[2:3]
	v_lshl_add_u64 v[4:5], v[126:127], 0, v[4:5]
	v_exp_f32_e32 v2, v2
	v_exp_f32_e32 v3, v3
	s_nop 0
	v_pk_add_f32 v[2:3], v[2:3], 1.0 op_sel_hi:[1,0]
	s_nop 0
	v_rcp_f32_e32 v2, v2
	v_rcp_f32_e32 v3, v3
	s_nop 0
	v_pk_mul_f32 v[0:1], v[0:1], v[2:3]
	s_nop 0
	v_cvt_pk_bf16_f32 v0, v0, v1
	ds_write_b16 v215, v0 offset:512
	ds_write_b16_d16_hi v215, v0 offset:544
	s_waitcnt lgkmcnt(4)
	v_lshlrev_b32_e32 v1, 16, v11
	v_lshlrev_b32_e32 v0, 16, v10
	v_pk_fma_f32 v[0:1], v[176:177], v[0:1], v[6:7]
	s_nop 0
	v_pk_mul_f32 v[2:3], v[0:1], v[0:1]
	s_nop 0
	v_pk_fma_f32 v[2:3], v[2:3], s[20:21], v[128:129] op_sel_hi:[1,0,0] neg_lo:[1,0,0] neg_hi:[1,0,0]
	s_nop 0
	v_pk_mul_f32 v[2:3], v[0:1], v[2:3]
	s_nop 0
	v_exp_f32_e32 v2, v2
	v_exp_f32_e32 v3, v3
	s_nop 0
	v_pk_add_f32 v[2:3], v[2:3], 1.0 op_sel_hi:[1,0]
	s_nop 0
	v_rcp_f32_e32 v2, v2
	v_rcp_f32_e32 v3, v3
	s_nop 0
	v_pk_mul_f32 v[0:1], v[0:1], v[2:3]
	s_nop 0
	v_cvt_pk_bf16_f32 v0, v0, v1
	ds_write_b16 v215, v0 offset:576
	ds_write_b16_d16_hi v215, v0 offset:608
	s_waitcnt lgkmcnt(0)
	ds_read_b128 v[0:3], v147
	s_waitcnt lgkmcnt(0)
	global_store_dwordx4 v[4:5], v[0:3], off
	s_nop 1
	v_mfma_f32_32x32x16_bf16 v[0:15], v[100:103], v[76:79], 0
	s_waitcnt lgkmcnt(0)
	ds_write_b128 v212, v[100:103]
	v_cvt_pk_bf16_f32 v100, v48, v16
	v_cvt_pk_bf16_f32 v102, v49, v17
	s_nop 8
	v_pk_fma_f32 v[0:1], v[174:175], v[106:107], v[0:1]
	s_nop 0
	v_pk_fma_f32 v[0:1], v[170:171], v[110:111], v[0:1]
	v_pk_fma_f32 v[2:3], v[174:175], v[16:17], v[2:3]
	v_pk_fma_f32 v[18:19], v[180:181], v[0:1], v[18:19]
	v_cvt_pk_bf16_f32 v101, v32, v0
	v_cvt_pk_bf16_f32 v103, v33, v1
	v_pk_fma_f32 v[32:33], v[168:169], v[32:33], v[34:35]
	v_pk_fma_f32 v[18:19], v[170:171], v[16:17], v[18:19]
	v_pk_fma_f32 v[0:1], v[170:171], v[0:1], v[2:3]
	v_cvt_pk_bf16_f32 v2, v50, v18
	v_cvt_pk_bf16_f32 v3, v32, v0
	v_cvt_pk_bf16_f32 v16, v51, v19
	v_cvt_pk_bf16_f32 v17, v33, v1
	ds_write2_b64 v149, v[2:3], v[16:17] offset0:68 offset1:102
	v_pk_fma_f32 v[2:3], v[178:179], v[32:33], v[52:53]
	v_pk_fma_f32 v[16:17], v[172:173], v[50:51], v[36:37]
	v_pk_fma_f32 v[20:21], v[180:181], v[0:1], v[20:21]
	v_pk_fma_f32 v[4:5], v[174:175], v[18:19], v[4:5]
	v_pk_fma_f32 v[2:3], v[168:169], v[50:51], v[2:3]
	v_pk_fma_f32 v[16:17], v[168:169], v[32:33], v[16:17]
	v_pk_fma_f32 v[20:21], v[170:171], v[18:19], v[20:21]
	v_pk_fma_f32 v[0:1], v[170:171], v[0:1], v[4:5]
	v_cvt_pk_bf16_f32 v4, v2, v20
	v_cvt_pk_bf16_f32 v5, v16, v0
	v_cvt_pk_bf16_f32 v18, v3, v21
	v_cvt_pk_bf16_f32 v19, v17, v1
	ds_write2_b64 v149, v[4:5], v[18:19] offset0:136 offset1:170
	v_pk_fma_f32 v[4:5], v[178:179], v[16:17], v[54:55]
	v_pk_fma_f32 v[6:7], v[174:175], v[20:21], v[6:7]
	v_pk_fma_f32 v[4:5], v[168:169], v[2:3], v[4:5]
	v_pk_fma_f32 v[2:3], v[172:173], v[2:3], v[38:39]
	ds_write2_b64 v149, v[100:101], v[102:103] offset1:34
	v_pk_fma_f32 v[2:3], v[168:169], v[16:17], v[2:3]
	v_pk_fma_f32 v[16:17], v[180:181], v[0:1], v[22:23]
	v_pk_fma_f32 v[0:1], v[170:171], v[0:1], v[6:7]
	v_pk_fma_f32 v[16:17], v[170:171], v[20:21], v[16:17]
	v_cvt_pk_bf16_f32 v7, v2, v0
	v_cvt_pk_bf16_f32 v6, v4, v16
	v_cvt_pk_bf16_f32 v18, v5, v17
	v_cvt_pk_bf16_f32 v19, v3, v1
	ds_write2_b64 v149, v[6:7], v[18:19] offset0:204 offset1:238
	v_pk_fma_f32 v[6:7], v[178:179], v[2:3], v[56:57]
	v_pk_fma_f32 v[8:9], v[174:175], v[16:17], v[8:9]
	v_pk_fma_f32 v[6:7], v[168:169], v[4:5], v[6:7]
	v_pk_fma_f32 v[4:5], v[172:173], v[4:5], v[40:41]
	s_nop 0
	v_pk_fma_f32 v[2:3], v[168:169], v[2:3], v[4:5]
	v_pk_fma_f32 v[4:5], v[180:181], v[0:1], v[24:25]
	v_pk_fma_f32 v[0:1], v[170:171], v[0:1], v[8:9]
	v_pk_fma_f32 v[4:5], v[170:171], v[16:17], v[4:5]
	v_cvt_pk_bf16_f32 v9, v2, v0
	v_cvt_pk_bf16_f32 v8, v6, v4
	v_cvt_pk_bf16_f32 v16, v7, v5
	v_cvt_pk_bf16_f32 v17, v3, v1
	ds_write2_b64 v146, v[8:9], v[16:17] offset0:16 offset1:50
	v_pk_fma_f32 v[8:9], v[178:179], v[2:3], v[58:59]
	s_nop 0
	v_pk_fma_f32 v[8:9], v[168:169], v[6:7], v[8:9]
	v_pk_fma_f32 v[6:7], v[172:173], v[6:7], v[42:43]
	s_nop 0
	v_pk_fma_f32 v[2:3], v[168:169], v[2:3], v[6:7]
	v_pk_fma_f32 v[6:7], v[180:181], v[0:1], v[26:27]
	s_nop 0
	v_pk_fma_f32 v[6:7], v[170:171], v[4:5], v[6:7]
	v_pk_fma_f32 v[4:5], v[174:175], v[4:5], v[10:11]
	v_cvt_pk_bf16_f32 v10, v9, v7
	v_pk_fma_f32 v[0:1], v[170:171], v[0:1], v[4:5]
	v_cvt_pk_bf16_f32 v4, v8, v6
	v_cvt_pk_bf16_f32 v5, v2, v0
	v_cvt_pk_bf16_f32 v11, v3, v1
	ds_write2_b64 v146, v[4:5], v[10:11] offset0:84 offset1:118
	v_pk_fma_f32 v[4:5], v[178:179], v[2:3], v[60:61]
	s_nop 0
	v_pk_fma_f32 v[4:5], v[168:169], v[8:9], v[4:5]
	v_pk_fma_f32 v[8:9], v[172:173], v[8:9], v[44:45]
	s_nop 0
	v_pk_fma_f32 v[2:3], v[168:169], v[2:3], v[8:9]
	v_pk_fma_f32 v[8:9], v[180:181], v[0:1], v[28:29]
	s_nop 0
	v_pk_fma_f32 v[8:9], v[170:171], v[6:7], v[8:9]
	v_pk_fma_f32 v[6:7], v[174:175], v[6:7], v[12:13]
	v_cvt_pk_bf16_f32 v10, v5, v9
	v_pk_fma_f32 v[0:1], v[170:171], v[0:1], v[6:7]
	v_cvt_pk_bf16_f32 v6, v4, v8
	v_cvt_pk_bf16_f32 v7, v2, v0
	v_cvt_pk_bf16_f32 v11, v3, v1
	ds_write2_b64 v146, v[6:7], v[10:11] offset0:152 offset1:186
	v_pk_fma_f32 v[6:7], v[178:179], v[2:3], v[62:63]
	s_waitcnt vmcnt(6)
; #define LAS __attribute__((address_space(3)))
; #define LDS_WAIT() asm volatile("s_waitcnt lgkmcnt(0)" ::: "memory")
; __device__ __forceinline__ void ssm_phase(Frame& F) {
;     ...
; #pragma unroll
;             for (int s = 0; s < 8; ++s) {
;                 *(LAS bf16x8*)(ut + l31 * 32 + 16 * h) = afr[s];
;                 const f32x16 D0 = __builtin_amdgcn_mfma_f32_32x32x16_bf16(afr[s], bfrag[0], z, 0, 0, 0), D1 = __builtin_amdgcn_mfma_f32_32x32x16_bf16(afr[s], bfrag[1], z, 0, 0, 0),
;                              D2 = __builtin_amdgcn_mfma_f32_32x32x16_bf16(afr[s], bfrag[2], z, 0, 0, 0), D3 = __builtin_amdgcn_mfma_f32_32x32x16_bf16(afr[s], bfrag[3], z, 0, 0, 0);
; #pragma unroll
;                 for (int t = 0; t < 8; ++t) {
;                     const f2v d0 = {D0[2 * t], D0[2 * t + 1]}, d1 = {D1[2 * t], D1[2 * t + 1]}, d2 = {D2[2 * t], D2[2 * t + 1]}, d3 = {D3[2 * t], D3[2 * t + 1]};
;                     const f2v nr0 = fma2(AR0, Sre0, fma2(NAI0, Sim0, d0)), ni0 = fma2(AR0, Sim0, fma2(AI0, Sre0, d2));
;                     const f2v nr1 = fma2(AR1, Sre1, fma2(NAI1, Sim1, d1)), ni1 = fma2(AR1, Sim1, fma2(AI1, Sre1, d3));
;                     Sre0 = nr0; Sim0 = ni0; Sre1 = nr1; Sim1 = ni1;
; #pragma unroll
;                     for (int e = 0; e < 2; ++e) { v2u w; w.x = cvt2(nr0[e], nr1[e]); w.y = cvt2(ni0[e], ni1[e]); *(LAS v2u*)(st + (16 * h + 2 * t + e) * 272 + 8 * l31) = w; }
;                 }
;                 LDS_WAIT(); asm volatile("" ::: "memory");
;                 f32x4 acc0 = (f32x4){0.f, 0.f, 0.f, 0.f}, acc1 = (f32x4){0.f, 0.f, 0.f, 0.f};
; #pragma unroll
;                 for (int ks = 0; ks < 4; ++ks) {
;                     const bf16x8 s0 = *(const LAS bf16x8*)(st + l15 * 272 + 64 * ks + 16 * qq), s1 = *(const LAS bf16x8*)(st + (16 + l15) * 272 + 64 * ks + 16 * qq);
;                     acc0 = __builtin_amdgcn_mfma_f32_16x16x32_bf16(s0, cfrag[ks], acc0, 0, 0, 0); acc1 = __builtin_amdgcn_mfma_f32_16x16x32_bf16(s1, cfrag[ks], acc1, 0, 0, 0); }
;                 float uu[2][4];
; #pragma unroll
;                 for (int rb = 0; rb < 2; ++rb)
; #pragma unroll
;                     for (int i2 = 0; i2 < 4; ++i2) uu[rb][i2] = bf1(*(const LAS bf16*)(ut + (i2 + 4 * rb + 8 * qq) * 32 + 2 * l15));
; #pragma unroll
;                 for (int rb = 0; rb < 2; ++rb)
; #pragma unroll
;                     for (int i2 = 0; i2 < 4; i2 += 2) {
	v_mfma_f32_32x32x16_bf16 v[48:63], v[96:99], v[64:67], 0
	v_fma_f32 v100, v168, v4, v6
	v_fma_f32 v101, v169, v5, v7
	v_fma_f32 v4, v172, v4, v46
	v_fma_f32 v5, v173, v5, v47
	v_fma_f32 v102, v168, v2, v4
	v_fma_f32 v103, v169, v3, v5
	v_pk_fma_f32 v[2:3], v[180:181], v[0:1], v[30:31]
	s_nop 4
	v_pk_fma_f32 v[48:49], v[178:179], v[102:103], v[48:49]
	v_pk_fma_f32 v[104:105], v[170:171], v[8:9], v[2:3]
	v_pk_fma_f32 v[2:3], v[174:175], v[8:9], v[14:15]
	v_mfma_f32_32x32x16_bf16 v[32:47], v[96:99], v[72:75], 0
	v_fma_f32 v106, v170, v0, v2
	v_fma_f32 v107, v171, v1, v3
	v_cvt_pk_bf16_f32 v0, v100, v104
	v_cvt_pk_bf16_f32 v1, v102, v106
	v_cvt_pk_bf16_f32 v2, v101, v105
	v_cvt_pk_bf16_f32 v3, v103, v107
	ds_write2_b64 v146, v[0:1], v[2:3] offset0:220 offset1:254
	s_waitcnt lgkmcnt(0)
	ds_read_b128 v[0:3], v213 offset:32768
	ds_read_b128 v[4:7], v213 offset:37120
	s_waitcnt lgkmcnt(1)
	v_mfma_f32_16x16x32_bf16 v[0:3], v[0:3], v[80:83], 0
	ds_read_b128 v[8:11], v213 offset:32832
	ds_read_b128 v[12:15], v213 offset:37184
	v_pk_fma_f32 v[32:33], v[172:173], v[100:101], v[32:33]
	v_pk_fma_f32 v[48:49], v[168:169], v[100:101], v[48:49]
	s_waitcnt lgkmcnt(1)
	v_mfma_f32_16x16x32_bf16 v[0:3], v[8:11], v[84:87], v[0:3]
	ds_read_b128 v[8:11], v213 offset:32896
	ds_read_b128 v[16:19], v213 offset:37248
	v_pk_fma_f32 v[32:33], v[168:169], v[102:103], v[32:33]
	v_pk_fma_f32 v[34:35], v[172:173], v[48:49], v[34:35]
	s_waitcnt lgkmcnt(1)
	v_mfma_f32_16x16x32_bf16 v[0:3], v[8:11], v[88:91], v[0:3]
	ds_read_b128 v[8:11], v213 offset:32960
	ds_read_b128 v[20:23], v213 offset:37312
	v_pk_fma_f32 v[50:51], v[178:179], v[32:33], v[50:51]
	s_waitcnt lgkmcnt(1)
	v_mfma_f32_16x16x32_bf16 v[0:3], v[8:11], v[92:95], v[0:3]
	ds_read_u16 v8, v214
	ds_read_u16 v9, v214 offset:32
	v_pk_fma_f32 v[50:51], v[168:169], v[48:49], v[50:51]
	s_waitcnt lgkmcnt(1)
	v_lshlrev_b32_e32 v8, 16, v8
	s_waitcnt lgkmcnt(0)
	v_lshlrev_b32_e32 v9, 16, v9
	s_nop 0
	v_pk_fma_f32 v[0:1], v[176:177], v[8:9], v[0:1]
	v_mfma_f32_16x16x32_bf16 v[4:7], v[4:7], v[80:83], 0
	v_mul_f32_e64 v8, v0, v0
	v_mul_f32_e64 v9, v1, v1
	v_pk_fma_f32 v[8:9], v[8:9], s[20:21], v[128:129] op_sel_hi:[1,0,0] neg_lo:[1,0,0] neg_hi:[1,0,0]
	v_mfma_f32_16x16x32_bf16 v[4:7], v[12:15], v[84:87], v[4:7]
	v_mul_f32_e64 v8, v0, v8
	v_mul_f32_e64 v9, v1, v9
	v_exp_f32_e32 v8, v8
	v_exp_f32_e32 v9, v9
	v_mfma_f32_16x16x32_bf16 v[4:7], v[16:19], v[88:91], v[4:7]
	v_add_f32_e64 v8, v8, 1.0
	v_add_f32_e64 v9, v9, 1.0
	v_rcp_f32_e32 v8, v8
	v_rcp_f32_e32 v9, v9
	v_mfma_f32_16x16x32_bf16 v[4:7], v[20:23], v[92:95], v[4:7]
	v_mul_f32_e64 v0, v0, v8
	v_mul_f32_e64 v1, v1, v9
	v_cvt_pk_bf16_f32 v0, v0, v1
	ds_read_u16 v8, v214 offset:128
	ds_read_u16 v9, v214 offset:160
	ds_write_b16 v215, v0
	ds_write_b16_d16_hi v215, v0 offset:32
	ds_read_u16 v0, v214 offset:64
	ds_read_u16 v1, v214 offset:96
	ds_read_u16 v10, v214 offset:192
	ds_read_u16 v11, v214 offset:224
	v_mfma_f32_32x32x16_bf16 v[16:31], v[96:99], v[68:71], 0
	s_waitcnt lgkmcnt(3)
	v_lshlrev_b32_e32 v0, 16, v0
	s_waitcnt lgkmcnt(2)
	v_lshlrev_b32_e32 v1, 16, v1
	v_fma_f32 v0, v176, v0, v2
	v_fma_f32 v1, v177, v1, v3
	v_pk_mul_f32 v[2:3], v[0:1], v[0:1]
	s_nop 4
	v_pk_fma_f32 v[16:17], v[180:181], v[106:107], v[16:17]
	v_pk_fma_f32 v[2:3], v[2:3], s[20:21], v[128:129] op_sel_hi:[1,0,0] neg_lo:[1,0,0] neg_hi:[1,0,0]
	v_pk_fma_f32 v[16:17], v[170:171], v[104:105], v[16:17]
	v_pk_mul_f32 v[2:3], v[0:1], v[2:3]
	s_nop 0
	v_exp_f32_e32 v2, v2
	v_exp_f32_e32 v3, v3
	s_nop 0
	v_pk_add_f32 v[2:3], v[2:3], 1.0 op_sel_hi:[1,0]
	s_nop 0
	v_rcp_f32_e32 v2, v2
	v_rcp_f32_e32 v3, v3
	s_nop 0
	v_pk_mul_f32 v[0:1], v[0:1], v[2:3]
	s_nop 0
	v_cvt_pk_bf16_f32 v0, v0, v1
	ds_write_b16 v215, v0 offset:64
	ds_write_b16_d16_hi v215, v0 offset:96
	v_lshlrev_b32_e32 v1, 16, v9
	v_lshlrev_b32_e32 v0, 16, v8
	v_pk_fma_f32 v[0:1], v[176:177], v[0:1], v[4:5]
	v_add_u32_e32 v4, v144, v148
	v_pk_mul_f32 v[2:3], v[0:1], v[0:1]
	v_ashrrev_i32_e32 v5, 31, v4
	v_pk_fma_f32 v[2:3], v[2:3], s[20:21], v[128:129] op_sel_hi:[1,0,0] neg_lo:[1,0,0] neg_hi:[1,0,0]
	v_lshlrev_b64 v[4:5], 11, v[4:5]
	v_pk_mul_f32 v[2:3], v[0:1], v[2:3]
	v_lshl_add_u64 v[4:5], v[126:127], 0, v[4:5]
	v_exp_f32_e32 v2, v2
	v_exp_f32_e32 v3, v3
	s_nop 0
	v_pk_add_f32 v[2:3], v[2:3], 1.0 op_sel_hi:[1,0]
	s_nop 0
	v_rcp_f32_e32 v2, v2
	v_rcp_f32_e32 v3, v3
	s_nop 0
	v_pk_mul_f32 v[0:1], v[0:1], v[2:3]
	s_nop 0
	v_cvt_pk_bf16_f32 v0, v0, v1
	ds_write_b16 v215, v0 offset:512
	ds_write_b16_d16_hi v215, v0 offset:544
	s_waitcnt lgkmcnt(4)
	v_lshlrev_b32_e32 v1, 16, v11
	v_lshlrev_b32_e32 v0, 16, v10
	v_pk_fma_f32 v[0:1], v[176:177], v[0:1], v[6:7]
	s_nop 0
	v_pk_mul_f32 v[2:3], v[0:1], v[0:1]
	s_nop 0
	v_pk_fma_f32 v[2:3], v[2:3], s[20:21], v[128:129] op_sel_hi:[1,0,0] neg_lo:[1,0,0] neg_hi:[1,0,0]
	s_nop 0
	v_pk_mul_f32 v[2:3], v[0:1], v[2:3]
	s_nop 0
	v_exp_f32_e32 v2, v2
	v_exp_f32_e32 v3, v3
	s_nop 0
	v_pk_add_f32 v[2:3], v[2:3], 1.0 op_sel_hi:[1,0]
	s_nop 0
	v_rcp_f32_e32 v2, v2
	v_rcp_f32_e32 v3, v3
	s_nop 0
	v_pk_mul_f32 v[0:1], v[0:1], v[2:3]
	s_nop 0
	v_cvt_pk_bf16_f32 v0, v0, v1
	ds_write_b16 v215, v0 offset:576
	ds_write_b16_d16_hi v215, v0 offset:608
	s_waitcnt lgkmcnt(0)
	ds_read_b128 v[0:3], v147
	s_waitcnt lgkmcnt(0)
	global_store_dwordx4 v[4:5], v[0:3], off
	s_nop 1
	v_mfma_f32_32x32x16_bf16 v[0:15], v[96:99], v[76:79], 0
	s_waitcnt lgkmcnt(0)
; #define LAS __attribute__((address_space(3)))
; __device__ __forceinline__ unsigned cvt2(float lo, float hi) { const f2_t v = {lo, hi}; return __builtin_bit_cast(unsigned, __builtin_convertvector(v, bf2_t)); }
; __device__ __forceinline__ f2v fma2(f2v a, f2v b, f2v c) { return __builtin_elementwise_fma(a, b, c); }
; __device__ __forceinline__ void ssm_phase(Frame& F) {
;     ...
; #pragma unroll
;             for (int s = 0; s < 8; ++s) {
;                 *(LAS bf16x8*)(ut + l31 * 32 + 16 * h) = afr[s];
;                 const f32x16 D0 = __builtin_amdgcn_mfma_f32_32x32x16_bf16(afr[s], bfrag[0], z, 0, 0, 0), D1 = __builtin_amdgcn_mfma_f32_32x32x16_bf16(afr[s], bfrag[1], z, 0, 0, 0),
;                              D2 = __builtin_amdgcn_mfma_f32_32x32x16_bf16(afr[s], bfrag[2], z, 0, 0, 0), D3 = __builtin_amdgcn_mfma_f32_32x32x16_bf16(afr[s], bfrag[3], z, 0, 0, 0);
; #pragma unroll
;                 for (int t = 0; t < 8; ++t) {
;                     const f2v d0 = {D0[2 * t], D0[2 * t + 1]}, d1 = {D1[2 * t], D1[2 * t + 1]}, d2 = {D2[2 * t], D2[2 * t + 1]}, d3 = {D3[2 * t], D3[2 * t + 1]};
;                     const f2v nr0 = fma2(AR0, Sre0, fma2(NAI0, Sim0, d0)), ni0 = fma2(AR0, Sim0, fma2(AI0, Sre0, d2));
;                     const f2v nr1 = fma2(AR1, Sre1, fma2(NAI1, Sim1, d1)), ni1 = fma2(AR1, Sim1, fma2(AI1, Sre1, d3));
;                     Sre0 = nr0; Sim0 = ni0; Sre1 = nr1; Sim1 = ni1;
; #pragma unroll
;                     for (int e = 0; e < 2; ++e) { v2u w; w.x = cvt2(nr0[e], nr1[e]); w.y = cvt2(ni0[e], ni1[e]); *(LAS v2u*)(st + (16 * h + 2 * t + e) * 272 + 8 * l31) = w; }
;                 }
	ds_write_b128 v212, v[96:99]
	v_cvt_pk_bf16_f32 v96, v48, v16
	v_cvt_pk_bf16_f32 v98, v49, v17
	s_nop 8
	v_pk_fma_f32 v[0:1], v[174:175], v[104:105], v[0:1]
	s_nop 0
	v_pk_fma_f32 v[0:1], v[170:171], v[106:107], v[0:1]
	v_pk_fma_f32 v[2:3], v[174:175], v[16:17], v[2:3]
	v_pk_fma_f32 v[18:19], v[180:181], v[0:1], v[18:19]
	v_cvt_pk_bf16_f32 v97, v32, v0
	v_cvt_pk_bf16_f32 v99, v33, v1
	v_pk_fma_f32 v[32:33], v[168:169], v[32:33], v[34:35]
	v_pk_fma_f32 v[18:19], v[170:171], v[16:17], v[18:19]
	v_pk_fma_f32 v[0:1], v[170:171], v[0:1], v[2:3]
	v_cvt_pk_bf16_f32 v2, v50, v18
	v_cvt_pk_bf16_f32 v3, v32, v0
	v_cvt_pk_bf16_f32 v16, v51, v19
	v_cvt_pk_bf16_f32 v17, v33, v1
	ds_write2_b64 v149, v[2:3], v[16:17] offset0:68 offset1:102
	v_pk_fma_f32 v[2:3], v[178:179], v[32:33], v[52:53]
	v_pk_fma_f32 v[16:17], v[172:173], v[50:51], v[36:37]
	v_pk_fma_f32 v[20:21], v[180:181], v[0:1], v[20:21]
	v_pk_fma_f32 v[4:5], v[174:175], v[18:19], v[4:5]
	v_pk_fma_f32 v[2:3], v[168:169], v[50:51], v[2:3]
	v_pk_fma_f32 v[16:17], v[168:169], v[32:33], v[16:17]
	v_pk_fma_f32 v[20:21], v[170:171], v[18:19], v[20:21]
	v_pk_fma_f32 v[0:1], v[170:171], v[0:1], v[4:5]
	v_cvt_pk_bf16_f32 v4, v2, v20
	v_cvt_pk_bf16_f32 v5, v16, v0
	v_cvt_pk_bf16_f32 v18, v3, v21
	v_cvt_pk_bf16_f32 v19, v17, v1
	ds_write2_b64 v149, v[4:5], v[18:19] offset0:136 offset1:170
	v_pk_fma_f32 v[4:5], v[178:179], v[16:17], v[54:55]
	v_pk_fma_f32 v[6:7], v[174:175], v[20:21], v[6:7]
	v_pk_fma_f32 v[4:5], v[168:169], v[2:3], v[4:5]
	v_pk_fma_f32 v[2:3], v[172:173], v[2:3], v[38:39]
	ds_write2_b64 v149, v[96:97], v[98:99] offset1:34
	v_pk_fma_f32 v[2:3], v[168:169], v[16:17], v[2:3]
	v_pk_fma_f32 v[16:17], v[180:181], v[0:1], v[22:23]
	v_pk_fma_f32 v[0:1], v[170:171], v[0:1], v[6:7]
	v_pk_fma_f32 v[16:17], v[170:171], v[20:21], v[16:17]
	v_cvt_pk_bf16_f32 v7, v2, v0
	v_cvt_pk_bf16_f32 v6, v4, v16
	v_cvt_pk_bf16_f32 v18, v5, v17
	v_cvt_pk_bf16_f32 v19, v3, v1
	ds_write2_b64 v149, v[6:7], v[18:19] offset0:204 offset1:238
	v_pk_fma_f32 v[6:7], v[178:179], v[2:3], v[56:57]
	v_pk_fma_f32 v[8:9], v[174:175], v[16:17], v[8:9]
	v_pk_fma_f32 v[6:7], v[168:169], v[4:5], v[6:7]
	v_pk_fma_f32 v[4:5], v[172:173], v[4:5], v[40:41]
	s_nop 0
	v_pk_fma_f32 v[2:3], v[168:169], v[2:3], v[4:5]
	v_pk_fma_f32 v[4:5], v[180:181], v[0:1], v[24:25]
	v_pk_fma_f32 v[0:1], v[170:171], v[0:1], v[8:9]
	v_pk_fma_f32 v[4:5], v[170:171], v[16:17], v[4:5]
	v_cvt_pk_bf16_f32 v9, v2, v0
	v_cvt_pk_bf16_f32 v8, v6, v4
	v_cvt_pk_bf16_f32 v16, v7, v5
	v_cvt_pk_bf16_f32 v17, v3, v1
	ds_write2_b64 v146, v[8:9], v[16:17] offset0:16 offset1:50
	v_pk_fma_f32 v[8:9], v[178:179], v[2:3], v[58:59]
	s_nop 0
	v_pk_fma_f32 v[8:9], v[168:169], v[6:7], v[8:9]
	v_pk_fma_f32 v[6:7], v[172:173], v[6:7], v[42:43]
	s_nop 0
	v_pk_fma_f32 v[2:3], v[168:169], v[2:3], v[6:7]
	v_pk_fma_f32 v[6:7], v[180:181], v[0:1], v[26:27]
	s_nop 0
	v_pk_fma_f32 v[6:7], v[170:171], v[4:5], v[6:7]
	v_pk_fma_f32 v[4:5], v[174:175], v[4:5], v[10:11]
	v_cvt_pk_bf16_f32 v10, v9, v7
	v_pk_fma_f32 v[0:1], v[170:171], v[0:1], v[4:5]
	v_cvt_pk_bf16_f32 v4, v8, v6
	v_cvt_pk_bf16_f32 v5, v2, v0
	v_cvt_pk_bf16_f32 v11, v3, v1
	ds_write2_b64 v146, v[4:5], v[10:11] offset0:84 offset1:118
	v_pk_fma_f32 v[4:5], v[178:179], v[2:3], v[60:61]
	s_nop 0
	v_pk_fma_f32 v[4:5], v[168:169], v[8:9], v[4:5]
	v_pk_fma_f32 v[8:9], v[172:173], v[8:9], v[44:45]
	s_nop 0
	v_pk_fma_f32 v[2:3], v[168:169], v[2:3], v[8:9]
	v_pk_fma_f32 v[8:9], v[180:181], v[0:1], v[28:29]
	s_nop 0
	v_pk_fma_f32 v[8:9], v[170:171], v[6:7], v[8:9]
	v_pk_fma_f32 v[6:7], v[174:175], v[6:7], v[12:13]
	v_cvt_pk_bf16_f32 v10, v5, v9
	v_pk_fma_f32 v[0:1], v[170:171], v[0:1], v[6:7]
	v_cvt_pk_bf16_f32 v6, v4, v8
	v_cvt_pk_bf16_f32 v7, v2, v0
	v_cvt_pk_bf16_f32 v11, v3, v1
	ds_write2_b64 v146, v[6:7], v[10:11] offset0:152 offset1:186
	v_pk_fma_f32 v[6:7], v[178:179], v[2:3], v[62:63]
	s_nop 0
	v_pk_fma_f32 v[6:7], v[168:169], v[4:5], v[6:7]
	v_pk_fma_f32 v[4:5], v[172:173], v[4:5], v[46:47]
	s_nop 0
	v_pk_fma_f32 v[2:3], v[168:169], v[2:3], v[4:5]
	v_pk_fma_f32 v[4:5], v[180:181], v[0:1], v[30:31]
	s_nop 0
	v_pk_fma_f32 v[4:5], v[170:171], v[8:9], v[4:5]
	v_pk_fma_f32 v[8:9], v[174:175], v[8:9], v[14:15]
	s_nop 0
	v_pk_fma_f32 v[0:1], v[170:171], v[0:1], v[8:9]
	v_cvt_pk_bf16_f32 v8, v6, v4
	v_cvt_pk_bf16_f32 v9, v2, v0
	v_cvt_pk_bf16_f32 v0, v7, v5
	v_cvt_pk_bf16_f32 v1, v3, v1
	ds_write2_b64 v146, v[8:9], v[0:1] offset0:220 offset1:254
	s_waitcnt lgkmcnt(0)
; #define GAS __attribute__((address_space(1)))
; #define LAS __attribute__((address_space(3)))
; #define LDS_WAIT() asm volatile("s_waitcnt lgkmcnt(0)" ::: "memory")
; __device__ __forceinline__ float bf1(bf16 v) { return __uint_as_float((unsigned)v << 16); }
; __device__ __forceinline__ void ssm_phase(Frame& F) {
;     ...
;     for (int task = F.vcu; task < (NBATCH / 2) * NG; task += F.G) {
;     ...
;                 f32x4 acc0 = (f32x4){0.f, 0.f, 0.f, 0.f}, acc1 = (f32x4){0.f, 0.f, 0.f, 0.f};
; #pragma unroll
;                 for (int ks = 0; ks < 4; ++ks) {
;                     const bf16x8 s0 = *(const LAS bf16x8*)(st + l15 * 272 + 64 * ks + 16 * qq), s1 = *(const LAS bf16x8*)(st + (16 + l15) * 272 + 64 * ks + 16 * qq);
;                     acc0 = __builtin_amdgcn_mfma_f32_16x16x32_bf16(s0, cfrag[ks], acc0, 0, 0, 0); acc1 = __builtin_amdgcn_mfma_f32_16x16x32_bf16(s1, cfrag[ks], acc1, 0, 0, 0); }
;                 float uu[2][4];
; #pragma unroll
;                 for (int rb = 0; rb < 2; ++rb)
; #pragma unroll
;                     for (int i2 = 0; i2 < 4; ++i2) uu[rb][i2] = bf1(*(const LAS bf16*)(ut + (i2 + 4 * rb + 8 * qq) * 32 + 2 * l15));
; #pragma unroll
;                 for (int rb = 0; rb < 2; ++rb)
; #pragma unroll
;                     for (int i2 = 0; i2 < 4; i2 += 2) {
;                         f2v y; y.x = (rb == 0 ? acc0[i2] : acc1[i2]) + dsk * uu[rb][i2]; y.y = (rb == 0 ? acc0[i2 + 1] : acc1[i2 + 1]) + dsk * uu[rb][i2 + 1];
;                         const f2v gq = gelu_tanh2(y); const unsigned w = cvt2(gq.x, gq.y);
;                         *(LAS bf16*)(yt + (16 * rb + 4 * qq + i2) * 32 + 2 * l15) = (bf16)(w & 0xffffu); *(LAS bf16*)(yt + (16 * rb + 4 * qq + i2 + 1) * 32 + 2 * l15) = (bf16)(w >> 16); }
;                 LDS_WAIT(); asm volatile("" ::: "memory");
;                 { const int R = lane >> 1, hf = lane & 1; const v4u yv = *(const LAS v4u*)(yt + lane * 16);
;                   const int chunk = F.wave + 8 * (2 * (R >> 4) + (R & 1)) + 32 * it, tok = 8 * s + ((R & 15) >> 1);
;                   *(GAS v4u*)(gb + ((size_t)(b * SEQ + chunk * 64 + tok)) * SW + g * SG + 8 * hf) = yv; }
;                 LDS_WAIT(); asm volatile("" ::: "memory");
;             }
;         }
;         __syncthreads();
	ds_read_b128 v[0:3], v213 offset:32768
	ds_read_b128 v[4:7], v213 offset:37120
	s_waitcnt lgkmcnt(1)
	v_mfma_f32_16x16x32_bf16 v[0:3], v[0:3], v[80:83], 0
	ds_read_b128 v[8:11], v213 offset:32832
	ds_read_b128 v[12:15], v213 offset:37184
	s_waitcnt lgkmcnt(1)
	v_mfma_f32_16x16x32_bf16 v[0:3], v[8:11], v[84:87], v[0:3]
	ds_read_b128 v[8:11], v213 offset:32896
	ds_read_b128 v[16:19], v213 offset:37248
	s_waitcnt lgkmcnt(1)
	v_mfma_f32_16x16x32_bf16 v[0:3], v[8:11], v[88:91], v[0:3]
	ds_read_b128 v[8:11], v213 offset:32960
	ds_read_b128 v[20:23], v213 offset:37312
	s_waitcnt lgkmcnt(1)
	v_mfma_f32_16x16x32_bf16 v[0:3], v[8:11], v[92:95], v[0:3]
	ds_read_u16 v8, v214
	ds_read_u16 v9, v214 offset:32
	s_waitcnt lgkmcnt(1)
	v_lshlrev_b32_e32 v8, 16, v8
	s_waitcnt lgkmcnt(0)
	v_lshlrev_b32_e32 v9, 16, v9
	s_nop 1
	v_pk_fma_f32 v[0:1], v[176:177], v[8:9], v[0:1]
	v_mfma_f32_16x16x32_bf16 v[4:7], v[4:7], v[80:83], 0
	v_mul_f32_e64 v8, v0, v0
	v_mul_f32_e64 v9, v1, v1
	v_pk_fma_f32 v[8:9], v[8:9], s[20:21], v[128:129] op_sel_hi:[1,0,0] neg_lo:[1,0,0] neg_hi:[1,0,0]
	v_mfma_f32_16x16x32_bf16 v[4:7], v[12:15], v[84:87], v[4:7]
	v_mul_f32_e64 v8, v0, v8
	v_mul_f32_e64 v9, v1, v9
	v_exp_f32_e32 v8, v8
	v_exp_f32_e32 v9, v9
	v_mfma_f32_16x16x32_bf16 v[4:7], v[16:19], v[88:91], v[4:7]
	v_add_f32_e64 v8, v8, 1.0
	v_add_f32_e64 v9, v9, 1.0
	v_rcp_f32_e32 v8, v8
	v_rcp_f32_e32 v9, v9
	v_mfma_f32_16x16x32_bf16 v[4:7], v[20:23], v[92:95], v[4:7]
	v_mul_f32_e64 v0, v0, v8
	v_mul_f32_e64 v1, v1, v9
	v_cvt_pk_bf16_f32 v0, v0, v1
	ds_read_u16 v8, v214 offset:128
	ds_read_u16 v9, v214 offset:160
	ds_write_b16 v215, v0
	ds_write_b16_d16_hi v215, v0 offset:32
	ds_read_u16 v0, v214 offset:64
	ds_read_u16 v1, v214 offset:96
	ds_read_u16 v10, v214 offset:192
	ds_read_u16 v11, v214 offset:224
	s_waitcnt lgkmcnt(3)
	v_lshlrev_b32_e32 v0, 16, v0
	s_waitcnt lgkmcnt(2)
	v_lshlrev_b32_e32 v1, 16, v1
	v_pk_fma_f32 v[0:1], v[176:177], v[0:1], v[2:3]
	s_nop 0
	v_pk_mul_f32 v[2:3], v[0:1], v[0:1]
	s_nop 0
	v_pk_fma_f32 v[2:3], v[2:3], s[20:21], v[128:129] op_sel_hi:[1,0,0] neg_lo:[1,0,0] neg_hi:[1,0,0]
	s_nop 0
	v_pk_mul_f32 v[2:3], v[0:1], v[2:3]
	s_nop 0
	v_exp_f32_e32 v2, v2
	v_exp_f32_e32 v3, v3
	s_nop 0
	v_pk_add_f32 v[2:3], v[2:3], 1.0 op_sel_hi:[1,0]
	s_nop 0
	v_rcp_f32_e32 v2, v2
	v_rcp_f32_e32 v3, v3
	s_nop 0
	v_pk_mul_f32 v[0:1], v[0:1], v[2:3]
	s_nop 0
	v_cvt_pk_bf16_f32 v0, v0, v1
	ds_write_b16 v215, v0 offset:64
	ds_write_b16_d16_hi v215, v0 offset:96
	v_lshlrev_b32_e32 v1, 16, v9
	v_lshlrev_b32_e32 v0, 16, v8
	v_pk_fma_f32 v[0:1], v[176:177], v[0:1], v[4:5]
	v_add_u32_e32 v4, v145, v148
	v_pk_mul_f32 v[2:3], v[0:1], v[0:1]
	v_ashrrev_i32_e32 v5, 31, v4
	v_pk_fma_f32 v[2:3], v[2:3], s[20:21], v[128:129] op_sel_hi:[1,0,0] neg_lo:[1,0,0] neg_hi:[1,0,0]
	v_lshlrev_b64 v[4:5], 11, v[4:5]
	v_pk_mul_f32 v[2:3], v[0:1], v[2:3]
	v_lshl_add_u64 v[4:5], v[126:127], 0, v[4:5]
	v_exp_f32_e32 v2, v2
	v_exp_f32_e32 v3, v3
	s_nop 0
	v_pk_add_f32 v[2:3], v[2:3], 1.0 op_sel_hi:[1,0]
	s_nop 0
	v_rcp_f32_e32 v2, v2
	v_rcp_f32_e32 v3, v3
	s_nop 0
	v_pk_mul_f32 v[0:1], v[0:1], v[2:3]
	s_nop 0
	v_cvt_pk_bf16_f32 v0, v0, v1
	ds_write_b16 v215, v0 offset:512
	ds_write_b16_d16_hi v215, v0 offset:544
	s_waitcnt lgkmcnt(4)
	v_lshlrev_b32_e32 v1, 16, v11
	v_lshlrev_b32_e32 v0, 16, v10
	v_pk_fma_f32 v[0:1], v[176:177], v[0:1], v[6:7]
	s_nop 0
	v_pk_mul_f32 v[2:3], v[0:1], v[0:1]
	s_nop 0
	v_pk_fma_f32 v[2:3], v[2:3], s[20:21], v[128:129] op_sel_hi:[1,0,0] neg_lo:[1,0,0] neg_hi:[1,0,0]
	s_nop 0
	v_pk_mul_f32 v[2:3], v[0:1], v[2:3]
	s_nop 0
	v_exp_f32_e32 v2, v2
	v_exp_f32_e32 v3, v3
	s_nop 0
	v_pk_add_f32 v[2:3], v[2:3], 1.0 op_sel_hi:[1,0]
	s_nop 0
	v_rcp_f32_e32 v2, v2
	v_rcp_f32_e32 v3, v3
	s_nop 0
	v_pk_mul_f32 v[0:1], v[0:1], v[2:3]
	s_nop 0
	v_cvt_pk_bf16_f32 v0, v0, v1
	ds_write_b16 v215, v0 offset:576
	ds_write_b16_d16_hi v215, v0 offset:608
	s_waitcnt lgkmcnt(0)
	ds_read_b128 v[0:3], v147
	s_waitcnt lgkmcnt(0)
	global_store_dwordx4 v[4:5], v[0:3], off
	s_waitcnt lgkmcnt(0)
	s_cbranch_vccz .LBB0_329
	s_add_i32 s0, s36, 0x80
	s_cmp_gt_i32 s36, -1
	s_mov_b32 s36, s0
	s_barrier
	s_cbranch_scc0 .LBB0_323
